# v26 without the nt hint on the swiglu output stores
# baseline (speedup 1.0000x reference)
.LBB0_255:
	v_lshl_add_u32 v146, s6, 8, v1
	v_ashrrev_i32_e32 v147, 31, v146
	v_lshlrev_b64 v[156:157], 6, v[146:147]
	v_lshl_add_u64 v[168:169], s[8:9], 0, v[156:157]
	v_mov_b64_e32 v[208:209], v[168:169]
	s_movk_i32 s98, 0x2000
	s_mov_b32 s99, 0
	v_lshl_add_u64 v[210:211], v[208:209], 0, s[98:99]
	global_load_dwordx4 v[192:195], v[208:209], off offset:1024
	global_load_dwordx4 v[196:199], v[208:209], off offset:1040
	global_load_dwordx4 v[200:203], v[208:209], off offset:1056
	global_load_dwordx4 v[204:207], v[208:209], off offset:1072
	global_load_dwordx4 v[176:179], v[208:209], off offset:2048
	global_load_dwordx4 v[180:183], v[208:209], off offset:2064
	global_load_dwordx4 v[184:187], v[208:209], off offset:2080
	global_load_dwordx4 v[188:191], v[208:209], off offset:2096
	v_mov_b32_e32 v174, v126
	v_mov_b32_e32 v175, v122
	v_mov_b32_e32 v122, v127
	v_mov_b32_e32 v126, v128
	v_mov_b32_e32 v127, v124
	v_mov_b32_e32 v124, v129
	v_mov_b32_e32 v128, v118
	v_mov_b32_e32 v129, v114
	v_mov_b32_e32 v114, v119
	v_lshl_or_b32 v172, s7, 7, v148
	v_ashrrev_i32_e32 v173, 31, v172
	s_waitcnt vmcnt(8)
	v_mov_b32_e32 v156, v228
	v_mov_b32_e32 v157, v229
	v_mov_b32_e32 v158, v230
	v_mov_b32_e32 v159, v231
	v_mov_b32_e32 v160, v232
	v_mov_b32_e32 v161, v233
	v_mov_b32_e32 v162, v234
	v_mov_b32_e32 v163, v235
	v_mov_b32_e32 v164, v236
	v_mov_b32_e32 v165, v237
	v_mov_b32_e32 v166, v238
	v_mov_b32_e32 v167, v239
	v_mov_b32_e32 v168, v240
	v_mov_b32_e32 v169, v241
	v_mov_b32_e32 v170, v242
	v_mov_b32_e32 v171, v243
	v_mov_b32_e32 v118, v157
	v_mov_b32_e32 v119, v158
	v_mov_b32_e32 v157, v159
	v_mov_b32_e32 v158, v161
	v_mov_b32_e32 v159, v162
	v_mov_b32_e32 v161, v163
	v_pk_add_f32 v[118:119], v[118:119], v[156:157]
	v_pk_add_f32 v[156:157], v[158:159], v[160:161]
	v_pk_add_f32 v[118:119], v[118:119], v[118:119] op_sel:[0,1] op_sel_hi:[1,0]
	v_pk_add_f32 v[156:157], v[156:157], v[156:157] op_sel:[0,1] op_sel_hi:[1,0]
	v_add_f32_e32 v162, v164, v165
	v_add_f32_e32 v164, v166, v167
	v_mov_b32_e32 v163, v170
	v_mov_b32_e32 v165, v171
	v_mov_b32_e32 v119, v168
	v_mov_b32_e32 v157, v169
	v_pk_add_f32 v[158:159], v[162:163], v[164:165]
	v_pk_add_f32 v[118:119], v[118:119], v[156:157]
	s_nop 0
	v_pk_add_f32 v[118:119], v[118:119], v[158:159]
	s_nop 0
	v_add_f32_e32 v118, v118, v119
	v_fmamk_f32 v118, v118, 0x3a800000, v152
	v_mul_f32_e32 v119, 0x4f800000, v118
	v_cmp_gt_f32_e32 vcc, s49, v118
	s_nop 1
	v_cndmask_b32_e32 v147, v118, v119, vcc
	v_sqrt_f32_e32 v156, v147
	v_mov_b32_e32 v118, v120
	v_mov_b32_e32 v119, v116
	v_mov_b32_e32 v116, v121
	v_add_u32_e32 v120, -1, v156
	v_add_u32_e32 v121, 1, v156
	v_fma_f32 v157, -v120, v156, v147
	v_fma_f32 v158, -v121, v156, v147
	v_cmp_ge_f32_e64 s[6:7], 0, v157
	s_nop 1
	v_cndmask_b32_e64 v120, v156, v120, s[6:7]
	v_cmp_lt_f32_e64 s[6:7], 0, v158
	s_nop 1
	v_cndmask_b32_e64 v120, v120, v121, s[6:7]
	v_mul_f32_e32 v121, 0x37800000, v120
	v_cndmask_b32_e32 v120, v120, v121, vcc
	v_cmp_class_f32_e32 vcc, v147, v153
	s_nop 1
	v_cndmask_b32_e32 v120, v120, v147, vcc
	v_div_scale_f32 v121, s[6:7], v120, v120, 1.0
	v_rcp_f32_e32 v147, v121
	v_div_scale_f32 v156, vcc, 1.0, v120, 1.0
	v_fma_f32 v157, -v121, v147, 1.0
	v_fmac_f32_e32 v147, v157, v147
	v_mul_f32_e32 v157, v156, v147
	v_fma_f32 v158, -v121, v157, v156
	v_fmac_f32_e32 v157, v158, v147
	v_fma_f32 v121, -v121, v157, v156
	v_div_fmas_f32 v121, v121, v147, v157
	v_div_fixup_f32 v120, v121, v120, 1.0
	v_pk_mul_f32 v[156:157], v[174:175], v[120:121] op_sel_hi:[1,0]
	v_pk_mul_f32 v[122:123], v[122:123], v[120:121] op_sel_hi:[1,0]
	v_pk_mul_f32 v[114:115], v[114:115], v[120:121] op_sel_hi:[1,0]
	v_pk_mul_f32 v[118:119], v[118:119], v[120:121] op_sel_hi:[1,0]
	v_pk_mul_f32 v[126:127], v[126:127], v[120:121] op_sel_hi:[1,0]
	v_pk_mul_f32 v[124:125], v[124:125], v[120:121] op_sel_hi:[1,0]
	v_pk_mul_f32 v[128:129], v[128:129], v[120:121] op_sel_hi:[1,0]
	v_pk_mul_f32 v[116:117], v[116:117], v[120:121] op_sel_hi:[1,0]
	v_mul_f32_e32 v120, 0xbfb8aa3b, v157
	v_mul_f32_e32 v121, 0xbfb8aa3b, v123
	v_mul_f32_e32 v160, 0xbfb8aa3b, v115
	v_mul_f32_e32 v161, 0xbfb8aa3b, v119
	v_mul_f32_e32 v147, 0xbfb8aa3b, v127
	v_mul_f32_e32 v158, 0xbfb8aa3b, v125
	v_mul_f32_e32 v159, 0xbfb8aa3b, v129
	v_mul_f32_e32 v162, 0xbfb8aa3b, v117
	v_exp_f32_e32 v120, v120
	v_exp_f32_e32 v121, v121
	v_exp_f32_e32 v160, v160
	v_exp_f32_e32 v161, v161
	v_exp_f32_e32 v147, v147
	v_exp_f32_e32 v158, v158
	v_exp_f32_e32 v159, v159
	v_exp_f32_e32 v162, v162
	v_add_f32_e32 v120, 1.0, v120
	v_add_f32_e32 v121, 1.0, v121
	v_add_f32_e32 v160, 1.0, v160
	v_add_f32_e32 v161, 1.0, v161
	v_add_f32_e32 v147, 1.0, v147
	v_add_f32_e32 v158, 1.0, v158
	v_add_f32_e32 v159, 1.0, v159
	v_add_f32_e32 v162, 1.0, v162
	v_rcp_f32_e32 v120, v120
	v_rcp_f32_e32 v121, v121
	v_rcp_f32_e32 v160, v160
	v_rcp_f32_e32 v161, v161
	v_rcp_f32_e32 v147, v147
	v_rcp_f32_e32 v158, v158
	v_rcp_f32_e32 v159, v159
	v_rcp_f32_e32 v162, v162
	v_mul_f32_e32 v120, v157, v120
	v_mul_f32_e32 v121, v123, v121
	v_mul_f32_e32 v115, v115, v160
	v_mul_f32_e32 v119, v119, v161
	v_mul_f32_e32 v123, v127, v147
	v_mul_f32_e32 v125, v125, v158
	v_mul_f32_e32 v127, v129, v159
	v_mul_f32_e32 v117, v117, v162
	v_mul_f32_e32 v120, v156, v120
	v_mul_f32_e32 v121, v122, v121
	v_mul_f32_e32 v114, v114, v115
	v_mul_f32_e32 v115, v118, v119
	v_mul_f32_e32 v122, v126, v123
	v_mul_f32_e32 v123, v124, v125
	v_mul_f32_e32 v124, v128, v127
	v_mul_f32_e32 v116, v116, v117
	v_cvt_pk_bf16_f32 v118, v120, v121
	v_cvt_pk_bf16_f32 v119, v122, v123
	v_cvt_pk_bf16_f32 v120, v124, v114
	v_cvt_pk_bf16_f32 v121, v115, v116
	v_mov_b64_e32 v[114:115], s[10:11]
	v_mad_i64_i32 v[122:123], s[6:7], v146, s50, v[114:115]
	v_lshlrev_b64 v[116:117], 1, v[172:173]
	v_lshl_add_u64 v[122:123], v[122:123], 0, v[116:117]
	global_store_dwordx4 v[122:123], v[118:121], off
	s_nop 1
	v_or_b32_e32 v118, 16, v146
	v_ashrrev_i32_e32 v119, 31, v118
	v_lshlrev_b64 v[120:121], 6, v[118:119]
	v_lshl_add_u64 v[128:129], s[8:9], 0, v[120:121]
	s_waitcnt vmcnt(5)
	v_mov_b32_e32 v120, v192
	v_mov_b32_e32 v121, v193
	v_mov_b32_e32 v122, v194
	v_mov_b32_e32 v123, v195
	v_mov_b32_e32 v124, v196
	v_mov_b32_e32 v125, v197
	v_mov_b32_e32 v126, v198
	v_mov_b32_e32 v127, v199
	v_mov_b32_e32 v156, v200
	v_mov_b32_e32 v157, v201
	v_mov_b32_e32 v158, v202
	v_mov_b32_e32 v159, v203
	v_mov_b32_e32 v160, v204
	v_mov_b32_e32 v161, v205
	v_mov_b32_e32 v162, v206
	v_mov_b32_e32 v163, v207
	global_load_dwordx4 v[192:195], v[208:209], off offset:3072
	global_load_dwordx4 v[196:199], v[208:209], off offset:3088
	global_load_dwordx4 v[200:203], v[208:209], off offset:3104
	global_load_dwordx4 v[204:207], v[208:209], off offset:3120
	v_mov_b32_e32 v128, v110
	v_mov_b32_e32 v110, v112
	v_mov_b32_e32 v112, v98
	v_mov_b32_e32 v129, v106
	v_mov_b32_e32 v106, v111
	v_mov_b32_e32 v111, v108
	v_mov_b32_e32 v108, v113
	v_mov_b32_e32 v113, v102
	v_mov_b32_e32 v164, v121
	v_mov_b32_e32 v165, v122
	v_mov_b32_e32 v121, v123
	v_mov_b32_e32 v122, v125
	v_mov_b32_e32 v123, v126
	v_mov_b32_e32 v125, v127
	v_pk_add_f32 v[120:121], v[164:165], v[120:121]
	v_pk_add_f32 v[122:123], v[122:123], v[124:125]
	v_pk_add_f32 v[120:121], v[120:121], v[120:121] op_sel:[0,1] op_sel_hi:[1,0]
	v_pk_add_f32 v[122:123], v[122:123], v[122:123] op_sel:[0,1] op_sel_hi:[1,0]
	v_add_f32_e32 v126, v156, v157
	v_add_f32_e32 v156, v158, v159
	v_mov_b32_e32 v127, v162
	v_mov_b32_e32 v157, v163
	v_mov_b32_e32 v121, v160
	v_mov_b32_e32 v123, v161
	v_pk_add_f32 v[124:125], v[126:127], v[156:157]
	v_pk_add_f32 v[120:121], v[120:121], v[122:123]
	s_nop 0
	v_pk_add_f32 v[120:121], v[120:121], v[124:125]
	s_nop 0
	v_add_f32_e32 v98, v120, v121
	v_fmamk_f32 v98, v98, 0x3a800000, v152
	v_mul_f32_e32 v102, 0x4f800000, v98
	v_cmp_gt_f32_e32 vcc, s49, v98
	s_nop 1
	v_cndmask_b32_e32 v119, v98, v102, vcc
	v_sqrt_f32_e32 v120, v119
	v_mov_b32_e32 v98, v100
	v_mov_b32_e32 v102, v99
	v_mov_b32_e32 v99, v104
	v_add_u32_e32 v100, -1, v120
	v_add_u32_e32 v104, 1, v120
	v_fma_f32 v121, -v100, v120, v119
	v_fma_f32 v122, -v104, v120, v119
	v_cmp_ge_f32_e64 s[6:7], 0, v121
	s_nop 1
	v_cndmask_b32_e64 v100, v120, v100, s[6:7]
	v_cmp_lt_f32_e64 s[6:7], 0, v122
	s_nop 1
	v_cndmask_b32_e64 v100, v100, v104, s[6:7]
	v_mul_f32_e32 v104, 0x37800000, v100
	v_cndmask_b32_e32 v100, v100, v104, vcc
	v_cmp_class_f32_e32 vcc, v119, v153
	v_mov_b32_e32 v104, v101
	s_nop 0
	v_cndmask_b32_e32 v100, v100, v119, vcc
	v_div_scale_f32 v119, s[6:7], v100, v100, 1.0
	v_rcp_f32_e32 v120, v119
	v_div_scale_f32 v101, vcc, 1.0, v100, 1.0
	v_fma_f32 v121, -v119, v120, 1.0
	v_fmac_f32_e32 v120, v121, v120
	v_mul_f32_e32 v121, v101, v120
	v_fma_f32 v122, -v119, v121, v101
	v_fmac_f32_e32 v121, v122, v120
	v_fma_f32 v101, -v119, v121, v101
	v_div_fmas_f32 v101, v101, v120, v121
	v_div_fixup_f32 v100, v101, v100, 1.0
	v_pk_mul_f32 v[106:107], v[106:107], v[100:101] op_sel_hi:[1,0]
	v_pk_mul_f32 v[110:111], v[110:111], v[100:101] op_sel_hi:[1,0]
	v_pk_mul_f32 v[108:109], v[108:109], v[100:101] op_sel_hi:[1,0]
	v_pk_mul_f32 v[120:121], v[128:129], v[100:101] op_sel_hi:[1,0]
	v_pk_mul_f32 v[112:113], v[112:113], v[100:101] op_sel_hi:[1,0]
	v_pk_mul_f32 v[102:103], v[102:103], v[100:101] op_sel_hi:[1,0]
	v_pk_mul_f32 v[98:99], v[98:99], v[100:101] op_sel_hi:[1,0]
	v_pk_mul_f32 v[100:101], v[104:105], v[100:101] op_sel_hi:[1,0]
	v_mul_f32_e32 v105, 0xbfb8aa3b, v107
	v_mul_f32_e32 v119, 0xbfb8aa3b, v111
	v_mul_f32_e32 v122, 0xbfb8aa3b, v109
	v_exp_f32_e32 v105, v105
	v_exp_f32_e32 v119, v119
	v_exp_f32_e32 v122, v122
	v_mul_f32_e32 v124, 0xbfb8aa3b, v103
	v_mul_f32_e32 v125, 0xbfb8aa3b, v99
	v_mul_f32_e32 v126, 0xbfb8aa3b, v101
	v_exp_f32_e32 v124, v124
	v_exp_f32_e32 v125, v125
	v_add_f32_e32 v105, 1.0, v105
	v_add_f32_e32 v119, 1.0, v119
	v_add_f32_e32 v122, 1.0, v122
	v_mul_f32_e32 v104, 0xbfb8aa3b, v121
	v_mul_f32_e32 v123, 0xbfb8aa3b, v113
	v_exp_f32_e32 v126, v126
	v_rcp_f32_e32 v105, v105
	v_rcp_f32_e32 v119, v119
	v_rcp_f32_e32 v122, v122
	v_exp_f32_e32 v104, v104
	v_exp_f32_e32 v123, v123
	v_add_f32_e32 v124, 1.0, v124
	v_add_f32_e32 v125, 1.0, v125
	v_add_f32_e32 v126, 1.0, v126
	v_rcp_f32_e32 v124, v124
	v_rcp_f32_e32 v125, v125
	v_mul_f32_e32 v105, v107, v105
	v_mul_f32_e32 v107, v111, v119
	v_mul_f32_e32 v109, v109, v122
	v_add_f32_e32 v104, 1.0, v104
	v_add_f32_e32 v123, 1.0, v123
	v_mul_f32_e32 v105, v106, v105
	v_mul_f32_e32 v106, v110, v107
	v_mul_f32_e32 v107, v108, v109
	v_rcp_f32_e32 v109, v126
	v_rcp_f32_e32 v104, v104
	v_rcp_f32_e32 v123, v123
	v_mul_f32_e32 v103, v103, v124
	v_mul_f32_e32 v99, v99, v125
	v_mul_f32_e32 v102, v102, v103
	v_mul_f32_e32 v103, v98, v99
	v_mul_f32_e32 v98, v101, v109
	v_mul_f32_e32 v104, v121, v104
	v_mul_f32_e32 v111, v113, v123
	v_mul_f32_e32 v101, v100, v98
	v_mul_f32_e32 v104, v120, v104
	v_mul_f32_e32 v108, v112, v111
	v_cvt_pk_bf16_f32 v98, v104, v105
	v_cvt_pk_bf16_f32 v99, v106, v107
	v_cvt_pk_bf16_f32 v100, v108, v102
	v_cvt_pk_bf16_f32 v101, v103, v101
	v_mad_i64_i32 v[102:103], s[6:7], v118, s50, v[114:115]
	v_lshl_add_u64 v[102:103], v[102:103], 0, v[116:117]
	global_store_dwordx4 v[102:103], v[98:101], off
	s_nop 1
	v_or_b32_e32 v98, 32, v146
	v_ashrrev_i32_e32 v99, 31, v98
	v_lshlrev_b64 v[100:101], 6, v[98:99]
	v_lshl_add_u64 v[112:113], s[8:9], 0, v[100:101]
	s_waitcnt vmcnt(6)
	v_mov_b32_e32 v100, v176
	v_mov_b32_e32 v101, v177
	v_mov_b32_e32 v102, v178
	v_mov_b32_e32 v103, v179
	v_mov_b32_e32 v104, v180
	v_mov_b32_e32 v105, v181
	v_mov_b32_e32 v106, v182
	v_mov_b32_e32 v107, v183
	v_mov_b32_e32 v108, v184
	v_mov_b32_e32 v109, v185
	v_mov_b32_e32 v110, v186
	v_mov_b32_e32 v111, v187
	v_mov_b32_e32 v118, v188
	v_mov_b32_e32 v119, v189
	v_mov_b32_e32 v120, v190
	v_mov_b32_e32 v121, v191
	global_load_dwordx4 v[176:179], v[210:211], off
	global_load_dwordx4 v[180:183], v[210:211], off offset:16
	global_load_dwordx4 v[184:187], v[210:211], off offset:32
	global_load_dwordx4 v[188:191], v[210:211], off offset:48
	v_mov_b32_e32 v112, v94
	v_mov_b32_e32 v94, v96
	v_mov_b32_e32 v96, v82
	v_mov_b32_e32 v113, v90
	v_mov_b32_e32 v90, v95
	v_mov_b32_e32 v95, v92
	v_mov_b32_e32 v92, v97
	v_mov_b32_e32 v97, v86
	v_mov_b32_e32 v122, v101
	v_mov_b32_e32 v123, v102
	v_mov_b32_e32 v101, v103
	v_mov_b32_e32 v102, v105
	v_mov_b32_e32 v103, v106
	v_mov_b32_e32 v105, v107
	v_pk_add_f32 v[100:101], v[122:123], v[100:101]
	v_pk_add_f32 v[102:103], v[102:103], v[104:105]
	v_pk_add_f32 v[100:101], v[100:101], v[100:101] op_sel:[0,1] op_sel_hi:[1,0]
	v_pk_add_f32 v[102:103], v[102:103], v[102:103] op_sel:[0,1] op_sel_hi:[1,0]
	v_add_f32_e32 v106, v108, v109
	v_add_f32_e32 v108, v110, v111
	v_mov_b32_e32 v107, v120
	v_mov_b32_e32 v109, v121
	v_mov_b32_e32 v101, v118
	v_mov_b32_e32 v103, v119
	v_pk_add_f32 v[104:105], v[106:107], v[108:109]
	v_pk_add_f32 v[100:101], v[100:101], v[102:103]
	s_nop 0
	v_pk_add_f32 v[100:101], v[100:101], v[104:105]
	s_nop 0
	v_add_f32_e32 v82, v100, v101
	v_fmamk_f32 v82, v82, 0x3a800000, v152
	v_mul_f32_e32 v86, 0x4f800000, v82
	v_cmp_gt_f32_e32 vcc, s49, v82
	s_nop 1
	v_cndmask_b32_e32 v99, v82, v86, vcc
	v_sqrt_f32_e32 v100, v99
	v_mov_b32_e32 v82, v84
	v_mov_b32_e32 v86, v83
	v_mov_b32_e32 v83, v88
	v_add_u32_e32 v84, -1, v100
	v_add_u32_e32 v88, 1, v100
	v_fma_f32 v101, -v84, v100, v99
	v_fma_f32 v102, -v88, v100, v99
	v_cmp_ge_f32_e64 s[6:7], 0, v101
	s_nop 1
	v_cndmask_b32_e64 v84, v100, v84, s[6:7]
	v_cmp_lt_f32_e64 s[6:7], 0, v102
	s_nop 1
	v_cndmask_b32_e64 v84, v84, v88, s[6:7]
	v_mul_f32_e32 v88, 0x37800000, v84
	v_cndmask_b32_e32 v84, v84, v88, vcc
	v_cmp_class_f32_e32 vcc, v99, v153
	v_mov_b32_e32 v88, v85
	s_nop 0
	v_cndmask_b32_e32 v84, v84, v99, vcc
	v_div_scale_f32 v99, s[6:7], v84, v84, 1.0
	v_rcp_f32_e32 v100, v99
	v_div_scale_f32 v85, vcc, 1.0, v84, 1.0
	v_fma_f32 v101, -v99, v100, 1.0
	v_fmac_f32_e32 v100, v101, v100
	v_mul_f32_e32 v101, v85, v100
	v_fma_f32 v102, -v99, v101, v85
	v_fmac_f32_e32 v101, v102, v100
	v_fma_f32 v85, -v99, v101, v85
	v_div_fmas_f32 v85, v85, v100, v101
	v_div_fixup_f32 v84, v85, v84, 1.0
	v_pk_mul_f32 v[90:91], v[90:91], v[84:85] op_sel_hi:[1,0]
	v_pk_mul_f32 v[94:95], v[94:95], v[84:85] op_sel_hi:[1,0]
	v_pk_mul_f32 v[92:93], v[92:93], v[84:85] op_sel_hi:[1,0]
	v_pk_mul_f32 v[100:101], v[112:113], v[84:85] op_sel_hi:[1,0]
	v_pk_mul_f32 v[96:97], v[96:97], v[84:85] op_sel_hi:[1,0]
	v_pk_mul_f32 v[86:87], v[86:87], v[84:85] op_sel_hi:[1,0]
	v_pk_mul_f32 v[82:83], v[82:83], v[84:85] op_sel_hi:[1,0]
	v_pk_mul_f32 v[84:85], v[88:89], v[84:85] op_sel_hi:[1,0]
	v_mul_f32_e32 v89, 0xbfb8aa3b, v91
	v_mul_f32_e32 v99, 0xbfb8aa3b, v95
	v_mul_f32_e32 v102, 0xbfb8aa3b, v93
	v_exp_f32_e32 v89, v89
	v_exp_f32_e32 v99, v99
	v_exp_f32_e32 v102, v102
	v_mul_f32_e32 v104, 0xbfb8aa3b, v87
	v_add_f32_e32 v89, 1.0, v89
	v_add_f32_e32 v99, 1.0, v99
	v_add_f32_e32 v102, 1.0, v102
	v_rcp_f32_e32 v89, v89
	v_rcp_f32_e32 v99, v99
	v_rcp_f32_e32 v102, v102
	v_mul_f32_e32 v105, 0xbfb8aa3b, v83
	v_mul_f32_e32 v89, v91, v89
	v_mul_f32_e32 v91, v95, v99
	v_mul_f32_e32 v93, v93, v102
	v_exp_f32_e32 v104, v104
	v_exp_f32_e32 v105, v105
	v_mul_f32_e32 v89, v90, v89
	v_mul_f32_e32 v90, v94, v91
	v_mul_f32_e32 v91, v92, v93
	v_mul_f32_e32 v93, 0xbfb8aa3b, v85
	v_mul_f32_e32 v88, 0xbfb8aa3b, v101
	v_mul_f32_e32 v103, 0xbfb8aa3b, v97
	v_exp_f32_e32 v93, v93
	v_exp_f32_e32 v88, v88
	v_exp_f32_e32 v103, v103
	v_add_f32_e32 v104, 1.0, v104
	v_add_f32_e32 v94, 1.0, v105
	v_rcp_f32_e32 v104, v104
	v_rcp_f32_e32 v94, v94
	v_add_f32_e32 v93, 1.0, v93
	v_add_f32_e32 v88, 1.0, v88
	v_add_f32_e32 v103, 1.0, v103
	v_rcp_f32_e32 v93, v93
	v_rcp_f32_e32 v88, v88
	v_rcp_f32_e32 v103, v103
	v_mul_f32_e32 v87, v87, v104
	v_mul_f32_e32 v83, v83, v94
	v_mul_f32_e32 v86, v86, v87
	v_mul_f32_e32 v87, v82, v83
	v_mul_f32_e32 v82, v85, v93
	v_mul_f32_e32 v88, v101, v88
	v_mul_f32_e32 v95, v97, v103
	v_mul_f32_e32 v85, v84, v82
	v_mul_f32_e32 v88, v100, v88
	v_mul_f32_e32 v92, v96, v95
	v_cvt_pk_bf16_f32 v82, v88, v89
	v_cvt_pk_bf16_f32 v83, v90, v91
	v_cvt_pk_bf16_f32 v84, v92, v86
	v_cvt_pk_bf16_f32 v85, v87, v85
	v_mad_i64_i32 v[86:87], s[6:7], v98, s50, v[114:115]
	v_lshl_add_u64 v[86:87], v[86:87], 0, v[116:117]
	global_store_dwordx4 v[86:87], v[82:85], off
	v_mov_b32_e32 v100, v78
	v_mov_b32_e32 v101, v74
	v_or_b32_e32 v82, 48, v146
	v_ashrrev_i32_e32 v83, 31, v82
	v_lshlrev_b64 v[84:85], 6, v[82:83]
	v_lshl_add_u64 v[96:97], s[8:9], 0, v[84:85]
	s_waitcnt vmcnt(6)
	v_mov_b32_e32 v84, v192
	v_mov_b32_e32 v85, v193
	v_mov_b32_e32 v86, v194
	v_mov_b32_e32 v87, v195
	v_mov_b32_e32 v88, v196
	v_mov_b32_e32 v89, v197
	v_mov_b32_e32 v90, v198
	v_mov_b32_e32 v91, v199
	v_mov_b32_e32 v92, v200
	v_mov_b32_e32 v93, v201
	v_mov_b32_e32 v94, v202
	v_mov_b32_e32 v95, v203
	v_mov_b32_e32 v96, v204
	v_mov_b32_e32 v97, v205
	v_mov_b32_e32 v98, v206
	v_mov_b32_e32 v99, v207
	global_load_dwordx4 v[192:195], v[210:211], off offset:1024
	global_load_dwordx4 v[196:199], v[210:211], off offset:1040
	global_load_dwordx4 v[200:203], v[210:211], off offset:1056
	global_load_dwordx4 v[204:207], v[210:211], off offset:1072
	v_mov_b32_e32 v74, v79
	v_mov_b32_e32 v78, v80
	v_mov_b32_e32 v79, v76
	v_mov_b32_e32 v76, v81
	v_mov_b32_e32 v80, v85
	v_mov_b32_e32 v81, v86
	v_mov_b32_e32 v85, v87
	v_mov_b32_e32 v86, v89
	v_mov_b32_e32 v87, v90
	v_mov_b32_e32 v89, v91
	v_pk_add_f32 v[80:81], v[80:81], v[84:85]
	v_pk_add_f32 v[84:85], v[86:87], v[88:89]
	v_pk_add_f32 v[80:81], v[80:81], v[80:81] op_sel:[0,1] op_sel_hi:[1,0]
	v_pk_add_f32 v[84:85], v[84:85], v[84:85] op_sel:[0,1] op_sel_hi:[1,0]
	v_add_f32_e32 v90, v92, v93
	v_add_f32_e32 v92, v94, v95
	v_mov_b32_e32 v91, v98
	v_mov_b32_e32 v93, v99
	v_mov_b32_e32 v81, v96
	v_mov_b32_e32 v85, v97
	v_pk_add_f32 v[86:87], v[90:91], v[92:93]
	v_pk_add_f32 v[80:81], v[80:81], v[84:85]
	s_nop 0
	v_pk_add_f32 v[80:81], v[80:81], v[86:87]
	s_nop 0
	v_add_f32_e32 v80, v80, v81
	v_fmamk_f32 v80, v80, 0x3a800000, v152
	v_mul_f32_e32 v81, 0x4f800000, v80
	v_cmp_gt_f32_e32 vcc, s49, v80
	s_nop 1
	v_cndmask_b32_e32 v83, v80, v81, vcc
	v_sqrt_f32_e32 v84, v83
	v_mov_b32_e32 v80, v66
	v_mov_b32_e32 v81, v70
	v_mov_b32_e32 v70, v67
	v_add_u32_e32 v66, -1, v84
	v_add_u32_e32 v67, 1, v84
	v_fma_f32 v85, -v66, v84, v83
	v_fma_f32 v86, -v67, v84, v83
	v_cmp_ge_f32_e64 s[6:7], 0, v85
	s_nop 1
	v_cndmask_b32_e64 v66, v84, v66, s[6:7]
	v_cmp_lt_f32_e64 s[6:7], 0, v86
	s_nop 1
	v_cndmask_b32_e64 v66, v66, v67, s[6:7]
	v_mul_f32_e32 v67, 0x37800000, v66
	v_cndmask_b32_e32 v66, v66, v67, vcc
	v_cmp_class_f32_e32 vcc, v83, v153
	s_nop 1
	v_cndmask_b32_e32 v67, v66, v83, vcc
	v_div_scale_f32 v83, s[6:7], v67, v67, 1.0
	v_rcp_f32_e32 v84, v83
	v_mov_b32_e32 v66, v68
	v_div_scale_f32 v68, vcc, 1.0, v67, 1.0
	v_fma_f32 v85, -v83, v84, 1.0
	v_fmac_f32_e32 v84, v85, v84
	v_mul_f32_e32 v85, v68, v84
	v_fma_f32 v86, -v83, v85, v68
	v_fmac_f32_e32 v85, v86, v84
	v_fma_f32 v68, -v83, v85, v68
	v_div_fmas_f32 v68, v68, v84, v85
	v_div_fixup_f32 v68, v68, v67, 1.0
	v_pk_mul_f32 v[84:85], v[100:101], v[68:69] op_sel_hi:[1,0]
	v_pk_mul_f32 v[74:75], v[74:75], v[68:69] op_sel_hi:[1,0]
	v_mul_f32_e32 v67, 0xbfb8aa3b, v85
	v_mul_f32_e32 v83, 0xbfb8aa3b, v75
	v_exp_f32_e32 v67, v67
	v_pk_mul_f32 v[78:79], v[78:79], v[68:69] op_sel_hi:[1,0]
	v_exp_f32_e32 v83, v83
	v_mul_f32_e32 v86, 0xbfb8aa3b, v79
	v_exp_f32_e32 v86, v86
	v_add_f32_e32 v67, 1.0, v67
	v_add_f32_e32 v83, 1.0, v83
	v_rcp_f32_e32 v67, v67
	v_rcp_f32_e32 v83, v83
	v_add_f32_e32 v86, 1.0, v86
	v_rcp_f32_e32 v86, v86
	v_mul_f32_e32 v67, v85, v67
	v_mul_f32_e32 v75, v75, v83
	v_mul_f32_e32 v83, v84, v67
	v_mov_b32_e32 v67, v72
	v_pk_mul_f32 v[66:67], v[66:67], v[68:69] op_sel_hi:[1,0]
	v_mul_f32_e32 v79, v79, v86
	v_mul_f32_e32 v72, 0xbfb8aa3b, v67
	v_pk_mul_f32 v[70:71], v[70:71], v[68:69] op_sel_hi:[1,0]
	v_mul_f32_e32 v74, v74, v75
	v_mul_f32_e32 v75, v78, v79
	v_exp_f32_e32 v78, v72
	v_mov_b32_e32 v72, v69
	v_pk_mul_f32 v[76:77], v[76:77], v[68:69] op_sel_hi:[1,0]
	v_pk_mul_f32 v[80:81], v[80:81], v[68:69] op_sel_hi:[1,0]
	v_mul_f32_e32 v89, 0xbfb8aa3b, v71
	v_pk_mul_f32 v[68:69], v[72:73], v[68:69] op_sel_hi:[1,0]
	v_exp_f32_e32 v89, v89
	v_mul_f32_e32 v72, 0xbfb8aa3b, v69
	v_mul_f32_e32 v87, 0xbfb8aa3b, v77
	v_mul_f32_e32 v88, 0xbfb8aa3b, v81
	v_exp_f32_e32 v72, v72
	v_exp_f32_e32 v87, v87
	v_exp_f32_e32 v88, v88
	v_add_f32_e32 v89, 1.0, v89
	v_add_f32_e32 v73, 1.0, v78
	v_rcp_f32_e32 v89, v89
	v_rcp_f32_e32 v73, v73
	v_add_f32_e32 v72, 1.0, v72
	v_add_f32_e32 v87, 1.0, v87
	v_add_f32_e32 v88, 1.0, v88
	v_rcp_f32_e32 v72, v72
	v_rcp_f32_e32 v87, v87
	v_rcp_f32_e32 v88, v88
	v_mul_f32_e32 v71, v71, v89
	v_mul_f32_e32 v67, v67, v73
	v_mul_f32_e32 v70, v70, v71
	v_mul_f32_e32 v71, v66, v67
	v_mul_f32_e32 v66, v69, v72
	v_mul_f32_e32 v77, v77, v87
	v_mul_f32_e32 v81, v81, v88
	v_mul_f32_e32 v69, v68, v66
	v_mul_f32_e32 v76, v76, v77
	v_mul_f32_e32 v77, v80, v81
	v_cvt_pk_bf16_f32 v66, v83, v74
	v_cvt_pk_bf16_f32 v67, v75, v76
	v_cvt_pk_bf16_f32 v68, v77, v70
	v_cvt_pk_bf16_f32 v69, v71, v69
	v_mad_i64_i32 v[70:71], s[6:7], v82, s50, v[114:115]
	v_lshl_add_u64 v[70:71], v[70:71], 0, v[116:117]
	global_store_dwordx4 v[70:71], v[66:69], off
	v_mov_b32_e32 v85, v58
	v_mov_b32_e32 v58, v63
	v_add_u32_e32 v66, 0x80, v146
	v_ashrrev_i32_e32 v67, 31, v66
	v_lshlrev_b64 v[68:69], 6, v[66:67]
	v_lshl_add_u64 v[80:81], s[8:9], 0, v[68:69]
	s_waitcnt vmcnt(6)
	v_mov_b32_e32 v68, v176
	v_mov_b32_e32 v69, v177
	v_mov_b32_e32 v70, v178
	v_mov_b32_e32 v71, v179
	v_mov_b32_e32 v72, v180
	v_mov_b32_e32 v73, v181
	v_mov_b32_e32 v74, v182
	v_mov_b32_e32 v75, v183
	v_mov_b32_e32 v76, v184
	v_mov_b32_e32 v77, v185
	v_mov_b32_e32 v78, v186
	v_mov_b32_e32 v79, v187
	v_mov_b32_e32 v80, v188
	v_mov_b32_e32 v81, v189
	v_mov_b32_e32 v82, v190
	v_mov_b32_e32 v83, v191
	global_load_dwordx4 v[176:179], v[210:211], off offset:2048
	global_load_dwordx4 v[180:183], v[210:211], off offset:2064
	global_load_dwordx4 v[184:187], v[210:211], off offset:2080
	global_load_dwordx4 v[188:191], v[210:211], off offset:2096
	v_mov_b32_e32 v63, v60
	v_mov_b32_e32 v84, v62
	v_mov_b32_e32 v62, v64
	v_mov_b32_e32 v86, v69
	v_mov_b32_e32 v87, v70
	v_mov_b32_e32 v69, v71
	v_mov_b32_e32 v70, v73
	v_mov_b32_e32 v71, v74
	v_mov_b32_e32 v73, v75
	v_pk_add_f32 v[68:69], v[86:87], v[68:69]
	v_pk_add_f32 v[70:71], v[70:71], v[72:73]
	v_pk_add_f32 v[68:69], v[68:69], v[68:69] op_sel:[0,1] op_sel_hi:[1,0]
	v_pk_add_f32 v[70:71], v[70:71], v[70:71] op_sel:[0,1] op_sel_hi:[1,0]
	v_add_f32_e32 v74, v76, v77
	v_add_f32_e32 v76, v78, v79
	v_mov_b32_e32 v75, v82
	v_mov_b32_e32 v77, v83
	v_mov_b32_e32 v69, v80
	v_mov_b32_e32 v71, v81
	v_pk_add_f32 v[72:73], v[74:75], v[76:77]
	v_pk_add_f32 v[68:69], v[68:69], v[70:71]
	s_nop 0
	v_pk_add_f32 v[68:69], v[68:69], v[72:73]
	s_nop 0
	v_add_f32_e32 v60, v68, v69
	v_fmamk_f32 v60, v60, 0x3a800000, v152
	v_mul_f32_e32 v64, 0x4f800000, v60
	v_cmp_gt_f32_e32 vcc, s49, v60
	s_nop 1
	v_cndmask_b32_e32 v67, v60, v64, vcc
	v_sqrt_f32_e32 v68, v67
	v_mov_b32_e32 v64, v50
	v_mov_b32_e32 v60, v65
	v_mov_b32_e32 v65, v54
	v_add_u32_e32 v50, -1, v68
	v_add_u32_e32 v54, 1, v68
	v_fma_f32 v69, -v50, v68, v67
	v_fma_f32 v70, -v54, v68, v67
	v_cmp_ge_f32_e64 s[6:7], 0, v69
	s_nop 1
	v_cndmask_b32_e64 v50, v68, v50, s[6:7]
	v_cmp_lt_f32_e64 s[6:7], 0, v70
	s_nop 1
	v_cndmask_b32_e64 v50, v50, v54, s[6:7]
	v_mul_f32_e32 v54, 0x37800000, v50
	v_cndmask_b32_e32 v50, v50, v54, vcc
	v_cmp_class_f32_e32 vcc, v67, v153
	v_mov_b32_e32 v54, v51
	s_nop 0
	v_cndmask_b32_e32 v50, v50, v67, vcc
	v_div_scale_f32 v67, s[6:7], v50, v50, 1.0
	v_rcp_f32_e32 v68, v67
	v_div_scale_f32 v51, vcc, 1.0, v50, 1.0
	v_fma_f32 v69, -v67, v68, 1.0
	v_fmac_f32_e32 v68, v69, v68
	v_mul_f32_e32 v69, v51, v68
	v_fma_f32 v70, -v67, v69, v51
	v_fmac_f32_e32 v69, v70, v68
	v_fma_f32 v51, -v67, v69, v51
	v_div_fmas_f32 v51, v51, v68, v69
	v_div_fixup_f32 v50, v51, v50, 1.0
	v_pk_mul_f32 v[68:69], v[84:85], v[50:51] op_sel_hi:[1,0]
	v_pk_mul_f32 v[58:59], v[58:59], v[50:51] op_sel_hi:[1,0]
	v_pk_mul_f32 v[62:63], v[62:63], v[50:51] op_sel_hi:[1,0]
	v_pk_mul_f32 v[60:61], v[60:61], v[50:51] op_sel_hi:[1,0]
	v_pk_mul_f32 v[64:65], v[64:65], v[50:51] op_sel_hi:[1,0]
	v_pk_mul_f32 v[54:55], v[54:55], v[50:51] op_sel_hi:[1,0]
	v_mul_f32_e32 v51, 0xbfb8aa3b, v69
	v_mul_f32_e32 v67, 0xbfb8aa3b, v59
	v_mul_f32_e32 v71, 0xbfb8aa3b, v61
	v_mul_f32_e32 v72, 0xbfb8aa3b, v65
	v_exp_f32_e32 v51, v51
	v_exp_f32_e32 v67, v67
	v_exp_f32_e32 v71, v71
	v_exp_f32_e32 v72, v72
	v_mul_f32_e32 v70, 0xbfb8aa3b, v63
	v_exp_f32_e32 v70, v70
	v_add_f32_e32 v51, 1.0, v51
	v_add_f32_e32 v67, 1.0, v67
	v_add_f32_e32 v71, 1.0, v71
	v_add_f32_e32 v72, 1.0, v72
	v_rcp_f32_e32 v51, v51
	v_mul_f32_e32 v73, 0xbfb8aa3b, v55
	v_rcp_f32_e32 v67, v67
	v_rcp_f32_e32 v71, v71
	v_rcp_f32_e32 v72, v72
	v_exp_f32_e32 v73, v73
	v_add_f32_e32 v70, 1.0, v70
	v_rcp_f32_e32 v70, v70
	v_mul_f32_e32 v51, v69, v51
	v_mul_f32_e32 v59, v59, v67
	v_mul_f32_e32 v61, v61, v71
	v_mul_f32_e32 v67, v68, v51
	v_mul_f32_e32 v51, v65, v72
	v_mul_f32_e32 v68, v58, v59
	v_mul_f32_e32 v60, v60, v61
	v_mul_f32_e32 v61, v64, v51
	v_add_f32_e32 v51, 1.0, v73
	v_mov_b32_e32 v58, v52
	v_mov_b32_e32 v59, v56
	v_mul_f32_e32 v63, v63, v70
	v_pk_mul_f32 v[58:59], v[58:59], v[50:51] op_sel_hi:[1,0]
	v_mul_f32_e32 v62, v62, v63
	v_rcp_f32_e32 v63, v51
	v_mul_f32_e32 v51, 0xbfb8aa3b, v59
	v_mov_b32_e32 v56, v53
	v_exp_f32_e32 v52, v51
	v_pk_mul_f32 v[50:51], v[56:57], v[50:51] op_sel_hi:[1,0]
	v_mul_f32_e32 v55, v55, v63
	v_mul_f32_e32 v53, 0xbfb8aa3b, v51
	v_exp_f32_e32 v53, v53
	v_add_f32_e32 v52, 1.0, v52
	v_rcp_f32_e32 v52, v52
	v_mul_f32_e32 v54, v54, v55
	v_add_f32_e32 v53, 1.0, v53
	v_rcp_f32_e32 v53, v53
	v_mul_f32_e32 v52, v59, v52
	v_mul_f32_e32 v55, v58, v52
	v_mov_b32_e32 v69, v42
	v_mul_f32_e32 v51, v51, v53
	v_mul_f32_e32 v53, v50, v51
	v_cvt_pk_bf16_f32 v50, v67, v68
	v_cvt_pk_bf16_f32 v51, v62, v60
	v_cvt_pk_bf16_f32 v52, v61, v54
	v_cvt_pk_bf16_f32 v53, v55, v53
	v_mad_i64_i32 v[54:55], s[6:7], v66, s50, v[114:115]
	v_add_u32_e32 v66, 0x90, v146
	v_lshl_add_u64 v[54:55], v[54:55], 0, v[116:117]
	v_ashrrev_i32_e32 v67, 31, v66
	global_store_dwordx4 v[54:55], v[50:53], off
	v_mov_b32_e32 v42, v47
	v_mov_b32_e32 v68, v46
	v_lshlrev_b64 v[50:51], 6, v[66:67]
	v_lshl_add_u64 v[62:63], s[8:9], 0, v[50:51]
	s_waitcnt vmcnt(6)
	v_mov_b32_e32 v50, v192
	v_mov_b32_e32 v51, v193
	v_mov_b32_e32 v52, v194
	v_mov_b32_e32 v53, v195
	v_mov_b32_e32 v54, v196
	v_mov_b32_e32 v55, v197
	v_mov_b32_e32 v56, v198
	v_mov_b32_e32 v57, v199
	v_mov_b32_e32 v58, v200
	v_mov_b32_e32 v59, v201
	v_mov_b32_e32 v60, v202
	v_mov_b32_e32 v61, v203
	v_mov_b32_e32 v62, v204
	v_mov_b32_e32 v63, v205
	v_mov_b32_e32 v64, v206
	v_mov_b32_e32 v65, v207
	global_load_dwordx4 v[192:195], v[210:211], off offset:3072
	global_load_dwordx4 v[196:199], v[210:211], off offset:3088
	global_load_dwordx4 v[200:203], v[210:211], off offset:3104
	global_load_dwordx4 v[204:207], v[210:211], off offset:3120
	v_mov_b32_e32 v46, v48
	v_mov_b32_e32 v70, v51
	v_mov_b32_e32 v71, v52
	v_mov_b32_e32 v51, v53
	v_mov_b32_e32 v52, v55
	v_mov_b32_e32 v53, v56
	v_mov_b32_e32 v55, v57
	v_pk_add_f32 v[50:51], v[70:71], v[50:51]
	v_pk_add_f32 v[52:53], v[52:53], v[54:55]
	v_pk_add_f32 v[50:51], v[50:51], v[50:51] op_sel:[0,1] op_sel_hi:[1,0]
	v_pk_add_f32 v[52:53], v[52:53], v[52:53] op_sel:[0,1] op_sel_hi:[1,0]
	v_add_f32_e32 v56, v58, v59
	v_add_f32_e32 v58, v60, v61
	v_mov_b32_e32 v57, v64
	v_mov_b32_e32 v59, v65
	v_mov_b32_e32 v51, v62
	v_mov_b32_e32 v53, v63
	v_pk_add_f32 v[54:55], v[56:57], v[58:59]
	v_pk_add_f32 v[50:51], v[50:51], v[52:53]
	s_nop 0
	v_pk_add_f32 v[50:51], v[50:51], v[54:55]
	s_nop 0
	v_add_f32_e32 v47, v50, v51
	v_fmamk_f32 v47, v47, 0x3a800000, v152
	v_mul_f32_e32 v48, 0x4f800000, v47
	v_cmp_gt_f32_e32 vcc, s49, v47
	s_nop 1
	v_cndmask_b32_e32 v50, v47, v48, vcc
	v_sqrt_f32_e32 v51, v50
	v_mov_b32_e32 v48, v34
	v_mov_b32_e32 v47, v44
	v_mov_b32_e32 v44, v49
	v_add_u32_e32 v34, -1, v51
	v_add_u32_e32 v49, 1, v51
	v_fma_f32 v52, -v34, v51, v50
	v_fma_f32 v53, -v49, v51, v50
	v_cmp_ge_f32_e64 s[6:7], 0, v52
	s_nop 1
	v_cndmask_b32_e64 v34, v51, v34, s[6:7]
	v_cmp_lt_f32_e64 s[6:7], 0, v53
	s_nop 1
	v_cndmask_b32_e64 v34, v34, v49, s[6:7]
	v_mul_f32_e32 v49, 0x37800000, v34
	v_cndmask_b32_e32 v34, v34, v49, vcc
	v_cmp_class_f32_e32 vcc, v50, v153
	v_mov_b32_e32 v49, v38
	s_nop 0
	v_cndmask_b32_e32 v34, v34, v50, vcc
	v_div_scale_f32 v50, s[6:7], v34, v34, 1.0
	v_rcp_f32_e32 v51, v50
	v_div_scale_f32 v38, vcc, 1.0, v34, 1.0
	v_fma_f32 v52, -v50, v51, 1.0
	v_fmac_f32_e32 v51, v52, v51
	v_mul_f32_e32 v52, v38, v51
	v_fma_f32 v53, -v50, v52, v38
	v_fmac_f32_e32 v52, v53, v51
	v_fma_f32 v38, -v50, v52, v38
	v_div_fmas_f32 v38, v38, v51, v52
	v_div_fixup_f32 v34, v38, v34, 1.0
	v_pk_mul_f32 v[50:51], v[68:69], v[34:35] op_sel_hi:[1,0]
	v_pk_mul_f32 v[42:43], v[42:43], v[34:35] op_sel_hi:[1,0]
	v_mul_f32_e32 v38, 0xbfb8aa3b, v51
	v_mul_f32_e32 v52, 0xbfb8aa3b, v43
	v_exp_f32_e32 v38, v38
	v_exp_f32_e32 v52, v52
	v_pk_mul_f32 v[48:49], v[48:49], v[34:35] op_sel_hi:[1,0]
	v_pk_mul_f32 v[44:45], v[44:45], v[34:35] op_sel_hi:[1,0]
	v_add_f32_e32 v38, 1.0, v38
	v_mul_f32_e32 v55, 0xbfb8aa3b, v49
	v_add_f32_e32 v52, 1.0, v52
	v_rcp_f32_e32 v38, v38
	v_exp_f32_e32 v55, v55
	v_rcp_f32_e32 v52, v52
	v_mul_f32_e32 v54, 0xbfb8aa3b, v45
	v_pk_mul_f32 v[46:47], v[46:47], v[34:35] op_sel_hi:[1,0]
	v_exp_f32_e32 v54, v54
	v_mul_f32_e32 v53, 0xbfb8aa3b, v47
	v_mul_f32_e32 v38, v51, v38
	v_exp_f32_e32 v53, v53
	v_mul_f32_e32 v43, v43, v52
	v_mul_f32_e32 v50, v50, v38
	v_add_f32_e32 v38, 1.0, v55
	v_mul_f32_e32 v51, v42, v43
	v_rcp_f32_e32 v42, v38
	v_mov_b32_e32 v38, v35
	v_add_f32_e32 v54, 1.0, v54
	v_pk_mul_f32 v[38:39], v[38:39], v[34:35] op_sel_hi:[1,0]
	v_rcp_f32_e32 v54, v54
	v_mul_f32_e32 v35, 0xbfb8aa3b, v39
	v_add_f32_e32 v53, 1.0, v53
	v_exp_f32_e32 v35, v35
	v_rcp_f32_e32 v53, v53
	v_mul_f32_e32 v45, v45, v54
	v_mul_f32_e32 v42, v49, v42
	v_mul_f32_e32 v44, v44, v45
	v_mul_f32_e32 v45, v48, v42
	v_add_f32_e32 v35, 1.0, v35
	v_mov_b32_e32 v42, v36
	v_mov_b32_e32 v43, v40
	v_mul_f32_e32 v47, v47, v53
	v_pk_mul_f32 v[42:43], v[42:43], v[34:35] op_sel_hi:[1,0]
	v_mul_f32_e32 v46, v46, v47
	v_rcp_f32_e32 v47, v35
	v_mul_f32_e32 v35, 0xbfb8aa3b, v43
	v_mov_b32_e32 v40, v37
	v_exp_f32_e32 v36, v35
	v_pk_mul_f32 v[34:35], v[40:41], v[34:35] op_sel_hi:[1,0]
	v_mul_f32_e32 v39, v39, v47
	v_mul_f32_e32 v37, 0xbfb8aa3b, v35
	v_exp_f32_e32 v37, v37
	v_add_f32_e32 v36, 1.0, v36
	v_rcp_f32_e32 v36, v36
	v_mul_f32_e32 v38, v38, v39
	v_add_f32_e32 v37, 1.0, v37
	v_rcp_f32_e32 v37, v37
	v_mul_f32_e32 v36, v43, v36
	v_mul_f32_e32 v39, v42, v36
	v_mov_b32_e32 v53, v26
	v_mul_f32_e32 v35, v35, v37
	v_mul_f32_e32 v37, v34, v35
	v_cvt_pk_bf16_f32 v34, v50, v51
	v_cvt_pk_bf16_f32 v35, v46, v44
	v_cvt_pk_bf16_f32 v36, v45, v38
	v_cvt_pk_bf16_f32 v37, v39, v37
	v_mad_i64_i32 v[38:39], s[6:7], v66, s50, v[114:115]
	v_add_u32_e32 v50, 0xa0, v146
	v_lshl_add_u64 v[38:39], v[38:39], 0, v[116:117]
	v_ashrrev_i32_e32 v51, 31, v50
	global_store_dwordx4 v[38:39], v[34:37], off
	v_mov_b32_e32 v26, v31
	v_mov_b32_e32 v52, v30
	v_lshlrev_b64 v[34:35], 6, v[50:51]
	v_lshl_add_u64 v[46:47], s[8:9], 0, v[34:35]
	s_waitcnt vmcnt(6)
	v_mov_b32_e32 v34, v176
	v_mov_b32_e32 v35, v177
	v_mov_b32_e32 v36, v178
	v_mov_b32_e32 v37, v179
	v_mov_b32_e32 v38, v180
	v_mov_b32_e32 v39, v181
	v_mov_b32_e32 v40, v182
	v_mov_b32_e32 v41, v183
	v_mov_b32_e32 v42, v184
	v_mov_b32_e32 v43, v185
	v_mov_b32_e32 v44, v186
	v_mov_b32_e32 v45, v187
	v_mov_b32_e32 v46, v188
	v_mov_b32_e32 v47, v189
	v_mov_b32_e32 v48, v190
	v_mov_b32_e32 v49, v191
	v_mov_b32_e32 v30, v32
	v_mov_b32_e32 v54, v35
	v_mov_b32_e32 v55, v36
	v_mov_b32_e32 v35, v37
	v_mov_b32_e32 v36, v39
	v_mov_b32_e32 v37, v40
	v_mov_b32_e32 v39, v41
	v_pk_add_f32 v[34:35], v[54:55], v[34:35]
	v_pk_add_f32 v[36:37], v[36:37], v[38:39]
	v_pk_add_f32 v[34:35], v[34:35], v[34:35] op_sel:[0,1] op_sel_hi:[1,0]
	v_pk_add_f32 v[36:37], v[36:37], v[36:37] op_sel:[0,1] op_sel_hi:[1,0]
	v_add_f32_e32 v40, v42, v43
	v_add_f32_e32 v42, v44, v45
	v_mov_b32_e32 v41, v48
	v_mov_b32_e32 v43, v49
	v_mov_b32_e32 v35, v46
	v_mov_b32_e32 v37, v47
	v_pk_add_f32 v[38:39], v[40:41], v[42:43]
	v_pk_add_f32 v[34:35], v[34:35], v[36:37]
	s_nop 0
	v_pk_add_f32 v[34:35], v[34:35], v[38:39]
	s_nop 0
	v_add_f32_e32 v31, v34, v35
	v_fmamk_f32 v31, v31, 0x3a800000, v152
	v_mul_f32_e32 v32, 0x4f800000, v31
	v_cmp_gt_f32_e32 vcc, s49, v31
	s_nop 1
	v_cndmask_b32_e32 v34, v31, v32, vcc
	v_sqrt_f32_e32 v35, v34
	v_mov_b32_e32 v32, v18
	v_mov_b32_e32 v31, v28
	v_mov_b32_e32 v28, v33
	v_add_u32_e32 v18, -1, v35
	v_add_u32_e32 v33, 1, v35
	v_fma_f32 v36, -v18, v35, v34
	v_fma_f32 v37, -v33, v35, v34
	v_cmp_ge_f32_e64 s[6:7], 0, v36
	s_nop 1
	v_cndmask_b32_e64 v18, v35, v18, s[6:7]
	v_cmp_lt_f32_e64 s[6:7], 0, v37
	s_nop 1
	v_cndmask_b32_e64 v18, v18, v33, s[6:7]
	v_mul_f32_e32 v33, 0x37800000, v18
	v_cndmask_b32_e32 v18, v18, v33, vcc
	v_cmp_class_f32_e32 vcc, v34, v153
	v_mov_b32_e32 v33, v22
	s_nop 0
	v_cndmask_b32_e32 v18, v18, v34, vcc
	v_div_scale_f32 v34, s[6:7], v18, v18, 1.0
	v_rcp_f32_e32 v35, v34
	v_div_scale_f32 v22, vcc, 1.0, v18, 1.0
	v_fma_f32 v36, -v34, v35, 1.0
	v_fmac_f32_e32 v35, v36, v35
	v_mul_f32_e32 v36, v22, v35
	v_fma_f32 v37, -v34, v36, v22
	v_fmac_f32_e32 v36, v37, v35
	v_fma_f32 v22, -v34, v36, v22
	v_div_fmas_f32 v22, v22, v35, v36
	v_div_fixup_f32 v18, v22, v18, 1.0
	v_pk_mul_f32 v[26:27], v[26:27], v[18:19] op_sel_hi:[1,0]
	v_pk_mul_f32 v[34:35], v[52:53], v[18:19] op_sel_hi:[1,0]
	v_mul_f32_e32 v36, 0xbfb8aa3b, v27
	v_mul_f32_e32 v22, 0xbfb8aa3b, v35
	v_exp_f32_e32 v36, v36
	v_exp_f32_e32 v22, v22
	v_pk_mul_f32 v[30:31], v[30:31], v[18:19] op_sel_hi:[1,0]
	v_pk_mul_f32 v[28:29], v[28:29], v[18:19] op_sel_hi:[1,0]
	v_add_f32_e32 v36, 1.0, v36
	v_add_f32_e32 v22, 1.0, v22
	v_rcp_f32_e32 v36, v36
	v_mul_f32_e32 v37, 0xbfb8aa3b, v31
	v_rcp_f32_e32 v22, v22
	v_exp_f32_e32 v37, v37
	v_mul_f32_e32 v27, v27, v36
	v_mul_f32_e32 v38, 0xbfb8aa3b, v29
	v_mul_f32_e32 v22, v35, v22
	v_mul_f32_e32 v35, v26, v27
	v_pk_mul_f32 v[26:27], v[32:33], v[18:19] op_sel_hi:[1,0]
	v_add_f32_e32 v37, 1.0, v37
	v_mul_f32_e32 v34, v34, v22
	v_mul_f32_e32 v22, 0xbfb8aa3b, v27
	v_rcp_f32_e32 v37, v37
	v_exp_f32_e32 v22, v22
	v_exp_f32_e32 v38, v38
	v_mov_b32_e32 v36, v10
	v_mul_f32_e32 v31, v31, v37
	v_add_f32_e32 v22, 1.0, v22
	v_mul_f32_e32 v30, v30, v31
	v_rcp_f32_e32 v31, v22
	v_mov_b32_e32 v22, v19
	v_add_f32_e32 v38, 1.0, v38
	v_pk_mul_f32 v[22:23], v[22:23], v[18:19] op_sel_hi:[1,0]
	v_rcp_f32_e32 v38, v38
	v_mul_f32_e32 v19, 0xbfb8aa3b, v23
	v_exp_f32_e32 v19, v19
	v_mul_f32_e32 v27, v27, v31
	v_mul_f32_e32 v29, v29, v38
	v_mul_f32_e32 v28, v28, v29
	v_mul_f32_e32 v29, v26, v27
	v_add_f32_e32 v19, 1.0, v19
	v_mov_b32_e32 v26, v20
	v_mov_b32_e32 v27, v24
	v_pk_mul_f32 v[26:27], v[26:27], v[18:19] op_sel_hi:[1,0]
	v_rcp_f32_e32 v31, v19
	v_mul_f32_e32 v19, 0xbfb8aa3b, v27
	v_mov_b32_e32 v24, v21
	v_exp_f32_e32 v20, v19
	v_pk_mul_f32 v[18:19], v[24:25], v[18:19] op_sel_hi:[1,0]
	v_mul_f32_e32 v23, v23, v31
	v_mul_f32_e32 v21, 0xbfb8aa3b, v19
	v_exp_f32_e32 v21, v21
	v_add_f32_e32 v20, 1.0, v20
	v_rcp_f32_e32 v20, v20
	v_mul_f32_e32 v22, v22, v23
	v_add_f32_e32 v21, 1.0, v21
	v_rcp_f32_e32 v21, v21
	v_mul_f32_e32 v20, v27, v20
	v_mul_f32_e32 v23, v26, v20
	v_mov_b32_e32 v37, v14
	v_mul_f32_e32 v19, v19, v21
	v_mul_f32_e32 v21, v18, v19
	v_cvt_pk_bf16_f32 v18, v34, v35
	v_cvt_pk_bf16_f32 v19, v30, v28
	v_cvt_pk_bf16_f32 v20, v29, v22
	v_cvt_pk_bf16_f32 v21, v23, v21
	v_mad_i64_i32 v[22:23], s[6:7], v50, s50, v[114:115]
	v_add_u32_e32 v34, 0xb0, v146
	v_lshl_add_u64 v[22:23], v[22:23], 0, v[116:117]
	v_ashrrev_i32_e32 v35, 31, v34
	global_store_dwordx4 v[22:23], v[18:21], off
	s_nop 1
	v_lshlrev_b64 v[18:19], 6, v[34:35]
	v_lshl_add_u64 v[30:31], s[8:9], 0, v[18:19]
	s_waitcnt vmcnt(2)
	v_mov_b32_e32 v18, v192
	v_mov_b32_e32 v19, v193
	v_mov_b32_e32 v20, v194
	v_mov_b32_e32 v21, v195
	v_mov_b32_e32 v22, v196
	v_mov_b32_e32 v23, v197
	v_mov_b32_e32 v24, v198
	v_mov_b32_e32 v25, v199
	v_mov_b32_e32 v26, v200
	v_mov_b32_e32 v27, v201
	v_mov_b32_e32 v28, v202
	v_mov_b32_e32 v29, v203
	v_mov_b32_e32 v30, v204
	v_mov_b32_e32 v31, v205
	v_mov_b32_e32 v32, v206
	v_mov_b32_e32 v33, v207
	v_mov_b32_e32 v38, v19
	v_mov_b32_e32 v39, v20
	v_mov_b32_e32 v19, v21
	v_mov_b32_e32 v20, v23
	v_mov_b32_e32 v21, v24
	v_mov_b32_e32 v23, v25
	v_pk_add_f32 v[18:19], v[38:39], v[18:19]
	v_pk_add_f32 v[20:21], v[20:21], v[22:23]
	v_pk_add_f32 v[18:19], v[18:19], v[18:19] op_sel:[0,1] op_sel_hi:[1,0]
	v_pk_add_f32 v[20:21], v[20:21], v[20:21] op_sel:[0,1] op_sel_hi:[1,0]
	v_add_f32_e32 v24, v26, v27
	v_add_f32_e32 v26, v28, v29
	v_mov_b32_e32 v25, v32
	v_mov_b32_e32 v27, v33
	v_mov_b32_e32 v19, v30
	v_mov_b32_e32 v21, v31
	v_pk_add_f32 v[22:23], v[24:25], v[26:27]
	v_pk_add_f32 v[18:19], v[18:19], v[20:21]
	s_nop 0
	v_pk_add_f32 v[18:19], v[18:19], v[22:23]
	s_nop 0
	v_add_f32_e32 v10, v18, v19
	v_fmamk_f32 v10, v10, 0x3a800000, v152
	v_mul_f32_e32 v14, 0x4f800000, v10
	v_cmp_gt_f32_e32 vcc, s49, v10
	s_nop 1
	v_cndmask_b32_e32 v18, v10, v14, vcc
	v_sqrt_f32_e32 v19, v18
	v_mov_b32_e32 v10, v12
	v_mov_b32_e32 v14, v11
	v_mov_b32_e32 v11, v16
	v_add_u32_e32 v12, -1, v19
	v_add_u32_e32 v16, 1, v19
	v_fma_f32 v20, -v12, v19, v18
	v_fma_f32 v21, -v16, v19, v18
	v_cmp_ge_f32_e64 s[6:7], 0, v20
	s_nop 1
	v_cndmask_b32_e64 v12, v19, v12, s[6:7]
	v_cmp_lt_f32_e64 s[6:7], 0, v21
	s_nop 1
	v_cndmask_b32_e64 v12, v12, v16, s[6:7]
	v_mul_f32_e32 v16, 0x37800000, v12
	v_cndmask_b32_e32 v12, v12, v16, vcc
	v_cmp_class_f32_e32 vcc, v18, v153
	v_mov_b32_e32 v16, v13
	s_nop 0
	v_cndmask_b32_e32 v12, v12, v18, vcc
	v_div_scale_f32 v18, s[6:7], v12, v12, 1.0
	v_rcp_f32_e32 v19, v18
	v_div_scale_f32 v13, vcc, 1.0, v12, 1.0
	v_fma_f32 v20, -v18, v19, 1.0
	v_fmac_f32_e32 v19, v20, v19
	v_mul_f32_e32 v20, v13, v19
	v_fma_f32 v21, -v18, v20, v13
	v_fmac_f32_e32 v20, v21, v19
	v_fma_f32 v13, -v18, v20, v13
	v_div_fmas_f32 v13, v13, v19, v20
	v_div_fixup_f32 v12, v13, v12, 1.0
	v_pk_mul_f32 v[18:19], v[36:37], v[12:13] op_sel_hi:[1,0]
	v_pk_mul_f32 v[14:15], v[14:15], v[12:13] op_sel_hi:[1,0]
	v_pk_mul_f32 v[10:11], v[10:11], v[12:13] op_sel_hi:[1,0]
	v_pk_mul_f32 v[16:17], v[16:17], v[12:13] op_sel_hi:[1,0]
	v_mul_f32_e32 v13, 0xbfb8aa3b, v19
	v_mul_f32_e32 v20, 0xbfb8aa3b, v15
	v_exp_f32_e32 v13, v13
	v_exp_f32_e32 v20, v20
	v_mul_f32_e32 v21, 0xbfb8aa3b, v11
	v_mul_f32_e32 v22, 0xbfb8aa3b, v17
	v_add_f32_e32 v13, 1.0, v13
	v_add_f32_e32 v20, 1.0, v20
	v_rcp_f32_e32 v13, v13
	v_rcp_f32_e32 v20, v20
	v_exp_f32_e32 v21, v21
	v_exp_f32_e32 v22, v22
	v_mul_f32_e32 v13, v19, v13
	v_mul_f32_e32 v15, v15, v20
	v_mul_f32_e32 v13, v18, v13
	v_mul_f32_e32 v18, v14, v15
	v_add_f32_e32 v14, 1.0, v21
	v_rcp_f32_e32 v19, v14
	v_add_f32_e32 v14, 1.0, v22
	v_rcp_f32_e32 v20, v14
	v_mov_b32_e32 v14, v2
	v_mov_b32_e32 v15, v6
	v_pk_mul_f32 v[14:15], v[14:15], v[12:13] op_sel_hi:[1,0]
	v_mul_f32_e32 v6, v11, v19
	v_mul_f32_e32 v2, 0xbfb8aa3b, v15
	v_exp_f32_e32 v2, v2
	v_mul_f32_e32 v10, v10, v6
	v_mov_b32_e32 v6, v3
	v_mul_f32_e32 v11, v17, v20
	v_add_f32_e32 v2, 1.0, v2
	v_rcp_f32_e32 v17, v2
	v_pk_mul_f32 v[2:3], v[6:7], v[12:13] op_sel_hi:[1,0]
	v_mul_f32_e32 v11, v16, v11
	v_mul_f32_e32 v6, 0xbfb8aa3b, v3
	v_exp_f32_e32 v6, v6
	v_mul_f32_e32 v7, v15, v17
	v_mul_f32_e32 v14, v14, v7
	v_mov_b32_e32 v7, v8
	v_add_f32_e32 v6, 1.0, v6
	v_rcp_f32_e32 v15, v6
	v_mov_b32_e32 v6, v4
	v_pk_mul_f32 v[6:7], v[6:7], v[12:13] op_sel_hi:[1,0]
	v_mov_b32_e32 v8, v5
	v_mul_f32_e32 v4, 0xbfb8aa3b, v7
	v_exp_f32_e32 v16, v4
	v_pk_mul_f32 v[4:5], v[8:9], v[12:13] op_sel_hi:[1,0]
	v_mul_f32_e32 v3, v3, v15
	v_mul_f32_e32 v8, 0xbfb8aa3b, v5
	v_exp_f32_e32 v8, v8
	v_add_f32_e32 v9, 1.0, v16
	v_rcp_f32_e32 v9, v9
	v_mul_f32_e32 v12, v2, v3
	v_add_f32_e32 v8, 1.0, v8
	v_rcp_f32_e32 v8, v8
	v_mul_f32_e32 v2, v7, v9
	v_mul_f32_e32 v6, v6, v2
	s_andn2_b64 vcc, exec, s[4:5]
	v_mul_f32_e32 v2, v5, v8
	v_mul_f32_e32 v5, v4, v2
	v_cvt_pk_bf16_f32 v2, v13, v18
	v_cvt_pk_bf16_f32 v3, v10, v11
	v_cvt_pk_bf16_f32 v4, v14, v12
	v_cvt_pk_bf16_f32 v5, v6, v5
	v_mad_i64_i32 v[6:7], s[6:7], v34, s50, v[114:115]
	v_lshl_add_u64 v[6:7], v[6:7], 0, v[116:117]
	s_mov_b64 s[4:5], -1
	global_store_dwordx4 v[6:7], v[2:5], off
	s_cbranch_vccnz .LBB0_248
	s_andn2_b64 vcc, exec, s[2:3]
	s_cbranch_vccnz .LBB0_247
	s_barrier
	s_branch .LBB0_247

.LBB0_2432:
	v_lshl_add_u32 v146, s6, 8, v1
	v_ashrrev_i32_e32 v147, 31, v146
	v_lshlrev_b64 v[156:157], 6, v[146:147]
	v_lshl_add_u64 v[168:169], s[10:11], 0, v[156:157]
	v_mov_b64_e32 v[208:209], v[168:169]
	s_movk_i32 s98, 0x2000
	s_mov_b32 s99, 0
	v_lshl_add_u64 v[210:211], v[208:209], 0, s[98:99]
	global_load_dwordx4 v[192:195], v[208:209], off offset:1024
	global_load_dwordx4 v[196:199], v[208:209], off offset:1040
	global_load_dwordx4 v[200:203], v[208:209], off offset:1056
	global_load_dwordx4 v[204:207], v[208:209], off offset:1072
	global_load_dwordx4 v[176:179], v[208:209], off offset:2048
	global_load_dwordx4 v[180:183], v[208:209], off offset:2064
	global_load_dwordx4 v[184:187], v[208:209], off offset:2080
	global_load_dwordx4 v[188:191], v[208:209], off offset:2096
	v_mov_b32_e32 v174, v126
	v_mov_b32_e32 v175, v122
	v_mov_b32_e32 v122, v127
	v_mov_b32_e32 v126, v128
	v_mov_b32_e32 v127, v124
	v_mov_b32_e32 v124, v129
	v_mov_b32_e32 v128, v118
	v_mov_b32_e32 v129, v114
	v_mov_b32_e32 v114, v119
	v_lshl_or_b32 v172, s7, 7, v148
	v_ashrrev_i32_e32 v173, 31, v172
	s_waitcnt vmcnt(8)
	v_mov_b32_e32 v156, v228
	v_mov_b32_e32 v157, v229
	v_mov_b32_e32 v158, v230
	v_mov_b32_e32 v159, v231
	v_mov_b32_e32 v160, v232
	v_mov_b32_e32 v161, v233
	v_mov_b32_e32 v162, v234
	v_mov_b32_e32 v163, v235
	v_mov_b32_e32 v164, v236
	v_mov_b32_e32 v165, v237
	v_mov_b32_e32 v166, v238
	v_mov_b32_e32 v167, v239
	v_mov_b32_e32 v168, v240
	v_mov_b32_e32 v169, v241
	v_mov_b32_e32 v170, v242
	v_mov_b32_e32 v171, v243
	v_mov_b32_e32 v118, v157
	v_mov_b32_e32 v119, v158
	v_mov_b32_e32 v157, v159
	v_mov_b32_e32 v158, v161
	v_mov_b32_e32 v159, v162
	v_mov_b32_e32 v161, v163
	v_pk_add_f32 v[118:119], v[118:119], v[156:157]
	v_pk_add_f32 v[156:157], v[158:159], v[160:161]
	v_pk_add_f32 v[118:119], v[118:119], v[118:119] op_sel:[0,1] op_sel_hi:[1,0]
	v_pk_add_f32 v[156:157], v[156:157], v[156:157] op_sel:[0,1] op_sel_hi:[1,0]
	v_add_f32_e32 v162, v164, v165
	v_add_f32_e32 v164, v166, v167
	v_mov_b32_e32 v163, v170
	v_mov_b32_e32 v165, v171
	v_mov_b32_e32 v119, v168
	v_mov_b32_e32 v157, v169
	v_pk_add_f32 v[158:159], v[162:163], v[164:165]
	v_pk_add_f32 v[118:119], v[118:119], v[156:157]
	s_nop 0
	v_pk_add_f32 v[118:119], v[118:119], v[158:159]
	s_nop 0
	v_add_f32_e32 v118, v118, v119
	v_fmamk_f32 v118, v118, 0x3a800000, v152
	v_mul_f32_e32 v119, 0x4f800000, v118
	v_cmp_gt_f32_e32 vcc, s49, v118
	s_nop 1
	v_cndmask_b32_e32 v147, v118, v119, vcc
	v_sqrt_f32_e32 v156, v147
	v_mov_b32_e32 v118, v120
	v_mov_b32_e32 v119, v116
	v_mov_b32_e32 v116, v121
	v_add_u32_e32 v120, -1, v156
	v_add_u32_e32 v121, 1, v156
	v_fma_f32 v157, -v120, v156, v147
	v_fma_f32 v158, -v121, v156, v147
	v_cmp_ge_f32_e64 s[6:7], 0, v157
	s_nop 1
	v_cndmask_b32_e64 v120, v156, v120, s[6:7]
	v_cmp_lt_f32_e64 s[6:7], 0, v158
	s_nop 1
	v_cndmask_b32_e64 v120, v120, v121, s[6:7]
	v_mul_f32_e32 v121, 0x37800000, v120
	v_cndmask_b32_e32 v120, v120, v121, vcc
	v_cmp_class_f32_e32 vcc, v147, v153
	s_nop 1
	v_cndmask_b32_e32 v120, v120, v147, vcc
	v_div_scale_f32 v121, s[6:7], v120, v120, 1.0
	v_rcp_f32_e32 v147, v121
	v_div_scale_f32 v156, vcc, 1.0, v120, 1.0
	v_fma_f32 v157, -v121, v147, 1.0
	v_fmac_f32_e32 v147, v157, v147
	v_mul_f32_e32 v157, v156, v147
	v_fma_f32 v158, -v121, v157, v156
	v_fmac_f32_e32 v157, v158, v147
	v_fma_f32 v121, -v121, v157, v156
	v_div_fmas_f32 v121, v121, v147, v157
	v_div_fixup_f32 v120, v121, v120, 1.0
	v_pk_mul_f32 v[156:157], v[174:175], v[120:121] op_sel_hi:[1,0]
	v_pk_mul_f32 v[122:123], v[122:123], v[120:121] op_sel_hi:[1,0]
	v_pk_mul_f32 v[114:115], v[114:115], v[120:121] op_sel_hi:[1,0]
	v_pk_mul_f32 v[118:119], v[118:119], v[120:121] op_sel_hi:[1,0]
	v_pk_mul_f32 v[126:127], v[126:127], v[120:121] op_sel_hi:[1,0]
	v_pk_mul_f32 v[124:125], v[124:125], v[120:121] op_sel_hi:[1,0]
	v_pk_mul_f32 v[128:129], v[128:129], v[120:121] op_sel_hi:[1,0]
	v_pk_mul_f32 v[116:117], v[116:117], v[120:121] op_sel_hi:[1,0]
	v_mul_f32_e32 v120, 0xbfb8aa3b, v157
	v_mul_f32_e32 v121, 0xbfb8aa3b, v123
	v_mul_f32_e32 v160, 0xbfb8aa3b, v115
	v_mul_f32_e32 v161, 0xbfb8aa3b, v119
	v_mul_f32_e32 v147, 0xbfb8aa3b, v127
	v_mul_f32_e32 v158, 0xbfb8aa3b, v125
	v_mul_f32_e32 v159, 0xbfb8aa3b, v129
	v_mul_f32_e32 v162, 0xbfb8aa3b, v117
	v_exp_f32_e32 v120, v120
	v_exp_f32_e32 v121, v121
	v_exp_f32_e32 v160, v160
	v_exp_f32_e32 v161, v161
	v_exp_f32_e32 v147, v147
	v_exp_f32_e32 v158, v158
	v_exp_f32_e32 v159, v159
	v_exp_f32_e32 v162, v162
	v_add_f32_e32 v120, 1.0, v120
	v_add_f32_e32 v121, 1.0, v121
	v_add_f32_e32 v160, 1.0, v160
	v_add_f32_e32 v161, 1.0, v161
	v_add_f32_e32 v147, 1.0, v147
	v_add_f32_e32 v158, 1.0, v158
	v_add_f32_e32 v159, 1.0, v159
	v_add_f32_e32 v162, 1.0, v162
	v_rcp_f32_e32 v120, v120
	v_rcp_f32_e32 v121, v121
	v_rcp_f32_e32 v160, v160
	v_rcp_f32_e32 v161, v161
	v_rcp_f32_e32 v147, v147
	v_rcp_f32_e32 v158, v158
	v_rcp_f32_e32 v159, v159
	v_rcp_f32_e32 v162, v162
	v_mul_f32_e32 v120, v157, v120
	v_mul_f32_e32 v121, v123, v121
	v_mul_f32_e32 v115, v115, v160
	v_mul_f32_e32 v119, v119, v161
	v_mul_f32_e32 v123, v127, v147
	v_mul_f32_e32 v125, v125, v158
	v_mul_f32_e32 v127, v129, v159
	v_mul_f32_e32 v117, v117, v162
	v_mul_f32_e32 v120, v156, v120
	v_mul_f32_e32 v121, v122, v121
	v_mul_f32_e32 v114, v114, v115
	v_mul_f32_e32 v115, v118, v119
	v_mul_f32_e32 v122, v126, v123
	v_mul_f32_e32 v123, v124, v125
	v_mul_f32_e32 v124, v128, v127
	v_mul_f32_e32 v116, v116, v117
	v_cvt_pk_bf16_f32 v118, v120, v121
	v_cvt_pk_bf16_f32 v119, v122, v123
	v_cvt_pk_bf16_f32 v120, v124, v114
	v_cvt_pk_bf16_f32 v121, v115, v116
	v_mov_b64_e32 v[114:115], s[8:9]
	v_mad_i64_i32 v[122:123], s[6:7], v146, s50, v[114:115]
	v_lshlrev_b64 v[116:117], 1, v[172:173]
	v_lshl_add_u64 v[122:123], v[122:123], 0, v[116:117]
	global_store_dwordx4 v[122:123], v[118:121], off
	s_nop 1
	v_or_b32_e32 v118, 16, v146
	v_ashrrev_i32_e32 v119, 31, v118
	v_lshlrev_b64 v[120:121], 6, v[118:119]
	v_lshl_add_u64 v[128:129], s[10:11], 0, v[120:121]
	s_waitcnt vmcnt(5)
	v_mov_b32_e32 v120, v192
	v_mov_b32_e32 v121, v193
	v_mov_b32_e32 v122, v194
	v_mov_b32_e32 v123, v195
	v_mov_b32_e32 v124, v196
	v_mov_b32_e32 v125, v197
	v_mov_b32_e32 v126, v198
	v_mov_b32_e32 v127, v199
	v_mov_b32_e32 v156, v200
	v_mov_b32_e32 v157, v201
	v_mov_b32_e32 v158, v202
	v_mov_b32_e32 v159, v203
	v_mov_b32_e32 v160, v204
	v_mov_b32_e32 v161, v205
	v_mov_b32_e32 v162, v206
	v_mov_b32_e32 v163, v207
	global_load_dwordx4 v[192:195], v[208:209], off offset:3072
	global_load_dwordx4 v[196:199], v[208:209], off offset:3088
	global_load_dwordx4 v[200:203], v[208:209], off offset:3104
	global_load_dwordx4 v[204:207], v[208:209], off offset:3120
	v_mov_b32_e32 v128, v110
	v_mov_b32_e32 v110, v112
	v_mov_b32_e32 v112, v98
	v_mov_b32_e32 v129, v106
	v_mov_b32_e32 v106, v111
	v_mov_b32_e32 v111, v108
	v_mov_b32_e32 v108, v113
	v_mov_b32_e32 v113, v102
	v_mov_b32_e32 v164, v121
	v_mov_b32_e32 v165, v122
	v_mov_b32_e32 v121, v123
	v_mov_b32_e32 v122, v125
	v_mov_b32_e32 v123, v126
	v_mov_b32_e32 v125, v127
	v_pk_add_f32 v[120:121], v[164:165], v[120:121]
	v_pk_add_f32 v[122:123], v[122:123], v[124:125]
	v_pk_add_f32 v[120:121], v[120:121], v[120:121] op_sel:[0,1] op_sel_hi:[1,0]
	v_pk_add_f32 v[122:123], v[122:123], v[122:123] op_sel:[0,1] op_sel_hi:[1,0]
	v_add_f32_e32 v126, v156, v157
	v_add_f32_e32 v156, v158, v159
	v_mov_b32_e32 v127, v162
	v_mov_b32_e32 v157, v163
	v_mov_b32_e32 v121, v160
	v_mov_b32_e32 v123, v161
	v_pk_add_f32 v[124:125], v[126:127], v[156:157]
	v_pk_add_f32 v[120:121], v[120:121], v[122:123]
	s_nop 0
	v_pk_add_f32 v[120:121], v[120:121], v[124:125]
	s_nop 0
	v_add_f32_e32 v98, v120, v121
	v_fmamk_f32 v98, v98, 0x3a800000, v152
	v_mul_f32_e32 v102, 0x4f800000, v98
	v_cmp_gt_f32_e32 vcc, s49, v98
	s_nop 1
	v_cndmask_b32_e32 v119, v98, v102, vcc
	v_sqrt_f32_e32 v120, v119
	v_mov_b32_e32 v98, v100
	v_mov_b32_e32 v102, v99
	v_mov_b32_e32 v99, v104
	v_add_u32_e32 v100, -1, v120
	v_add_u32_e32 v104, 1, v120
	v_fma_f32 v121, -v100, v120, v119
	v_fma_f32 v122, -v104, v120, v119
	v_cmp_ge_f32_e64 s[6:7], 0, v121
	s_nop 1
	v_cndmask_b32_e64 v100, v120, v100, s[6:7]
	v_cmp_lt_f32_e64 s[6:7], 0, v122
	s_nop 1
	v_cndmask_b32_e64 v100, v100, v104, s[6:7]
	v_mul_f32_e32 v104, 0x37800000, v100
	v_cndmask_b32_e32 v100, v100, v104, vcc
	v_cmp_class_f32_e32 vcc, v119, v153
	v_mov_b32_e32 v104, v101
	s_nop 0
	v_cndmask_b32_e32 v100, v100, v119, vcc
	v_div_scale_f32 v119, s[6:7], v100, v100, 1.0
	v_rcp_f32_e32 v120, v119
	v_div_scale_f32 v101, vcc, 1.0, v100, 1.0
	v_fma_f32 v121, -v119, v120, 1.0
	v_fmac_f32_e32 v120, v121, v120
	v_mul_f32_e32 v121, v101, v120
	v_fma_f32 v122, -v119, v121, v101
	v_fmac_f32_e32 v121, v122, v120
	v_fma_f32 v101, -v119, v121, v101
	v_div_fmas_f32 v101, v101, v120, v121
	v_div_fixup_f32 v100, v101, v100, 1.0
	v_pk_mul_f32 v[106:107], v[106:107], v[100:101] op_sel_hi:[1,0]
	v_pk_mul_f32 v[110:111], v[110:111], v[100:101] op_sel_hi:[1,0]
	v_pk_mul_f32 v[108:109], v[108:109], v[100:101] op_sel_hi:[1,0]
	v_pk_mul_f32 v[120:121], v[128:129], v[100:101] op_sel_hi:[1,0]
	v_pk_mul_f32 v[112:113], v[112:113], v[100:101] op_sel_hi:[1,0]
	v_pk_mul_f32 v[102:103], v[102:103], v[100:101] op_sel_hi:[1,0]
	v_pk_mul_f32 v[98:99], v[98:99], v[100:101] op_sel_hi:[1,0]
	v_pk_mul_f32 v[100:101], v[104:105], v[100:101] op_sel_hi:[1,0]
	v_mul_f32_e32 v105, 0xbfb8aa3b, v107
	v_mul_f32_e32 v119, 0xbfb8aa3b, v111
	v_mul_f32_e32 v122, 0xbfb8aa3b, v109
	v_exp_f32_e32 v105, v105
	v_exp_f32_e32 v119, v119
	v_exp_f32_e32 v122, v122
	v_mul_f32_e32 v124, 0xbfb8aa3b, v103
	v_mul_f32_e32 v125, 0xbfb8aa3b, v99
	v_mul_f32_e32 v126, 0xbfb8aa3b, v101
	v_exp_f32_e32 v124, v124
	v_exp_f32_e32 v125, v125
	v_add_f32_e32 v105, 1.0, v105
	v_add_f32_e32 v119, 1.0, v119
	v_add_f32_e32 v122, 1.0, v122
	v_mul_f32_e32 v104, 0xbfb8aa3b, v121
	v_mul_f32_e32 v123, 0xbfb8aa3b, v113
	v_exp_f32_e32 v126, v126
	v_rcp_f32_e32 v105, v105
	v_rcp_f32_e32 v119, v119
	v_rcp_f32_e32 v122, v122
	v_exp_f32_e32 v104, v104
	v_exp_f32_e32 v123, v123
	v_add_f32_e32 v124, 1.0, v124
	v_add_f32_e32 v125, 1.0, v125
	v_add_f32_e32 v126, 1.0, v126
	v_rcp_f32_e32 v124, v124
	v_rcp_f32_e32 v125, v125
	v_mul_f32_e32 v105, v107, v105
	v_mul_f32_e32 v107, v111, v119
	v_mul_f32_e32 v109, v109, v122
	v_add_f32_e32 v104, 1.0, v104
	v_add_f32_e32 v123, 1.0, v123
	v_mul_f32_e32 v105, v106, v105
	v_mul_f32_e32 v106, v110, v107
	v_mul_f32_e32 v107, v108, v109
	v_rcp_f32_e32 v109, v126
	v_rcp_f32_e32 v104, v104
	v_rcp_f32_e32 v123, v123
	v_mul_f32_e32 v103, v103, v124
	v_mul_f32_e32 v99, v99, v125
	v_mul_f32_e32 v102, v102, v103
	v_mul_f32_e32 v103, v98, v99
	v_mul_f32_e32 v98, v101, v109
	v_mul_f32_e32 v104, v121, v104
	v_mul_f32_e32 v111, v113, v123
	v_mul_f32_e32 v101, v100, v98
	v_mul_f32_e32 v104, v120, v104
	v_mul_f32_e32 v108, v112, v111
	v_cvt_pk_bf16_f32 v98, v104, v105
	v_cvt_pk_bf16_f32 v99, v106, v107
	v_cvt_pk_bf16_f32 v100, v108, v102
	v_cvt_pk_bf16_f32 v101, v103, v101
	v_mad_i64_i32 v[102:103], s[6:7], v118, s50, v[114:115]
	v_lshl_add_u64 v[102:103], v[102:103], 0, v[116:117]
	global_store_dwordx4 v[102:103], v[98:101], off
	s_nop 1
	v_or_b32_e32 v98, 32, v146
	v_ashrrev_i32_e32 v99, 31, v98
	v_lshlrev_b64 v[100:101], 6, v[98:99]
	v_lshl_add_u64 v[112:113], s[10:11], 0, v[100:101]
	s_waitcnt vmcnt(6)
	v_mov_b32_e32 v100, v176
	v_mov_b32_e32 v101, v177
	v_mov_b32_e32 v102, v178
	v_mov_b32_e32 v103, v179
	v_mov_b32_e32 v104, v180
	v_mov_b32_e32 v105, v181
	v_mov_b32_e32 v106, v182
	v_mov_b32_e32 v107, v183
	v_mov_b32_e32 v108, v184
	v_mov_b32_e32 v109, v185
	v_mov_b32_e32 v110, v186
	v_mov_b32_e32 v111, v187
	v_mov_b32_e32 v118, v188
	v_mov_b32_e32 v119, v189
	v_mov_b32_e32 v120, v190
	v_mov_b32_e32 v121, v191
	global_load_dwordx4 v[176:179], v[210:211], off
	global_load_dwordx4 v[180:183], v[210:211], off offset:16
	global_load_dwordx4 v[184:187], v[210:211], off offset:32
	global_load_dwordx4 v[188:191], v[210:211], off offset:48
	v_mov_b32_e32 v112, v94
	v_mov_b32_e32 v94, v96
	v_mov_b32_e32 v96, v82
	v_mov_b32_e32 v113, v90
	v_mov_b32_e32 v90, v95
	v_mov_b32_e32 v95, v92
	v_mov_b32_e32 v92, v97
	v_mov_b32_e32 v97, v86
	v_mov_b32_e32 v122, v101
	v_mov_b32_e32 v123, v102
	v_mov_b32_e32 v101, v103
	v_mov_b32_e32 v102, v105
	v_mov_b32_e32 v103, v106
	v_mov_b32_e32 v105, v107
	v_pk_add_f32 v[100:101], v[122:123], v[100:101]
	v_pk_add_f32 v[102:103], v[102:103], v[104:105]
	v_pk_add_f32 v[100:101], v[100:101], v[100:101] op_sel:[0,1] op_sel_hi:[1,0]
	v_pk_add_f32 v[102:103], v[102:103], v[102:103] op_sel:[0,1] op_sel_hi:[1,0]
	v_add_f32_e32 v106, v108, v109
	v_add_f32_e32 v108, v110, v111
	v_mov_b32_e32 v107, v120
	v_mov_b32_e32 v109, v121
	v_mov_b32_e32 v101, v118
	v_mov_b32_e32 v103, v119
	v_pk_add_f32 v[104:105], v[106:107], v[108:109]
	v_pk_add_f32 v[100:101], v[100:101], v[102:103]
	s_nop 0
	v_pk_add_f32 v[100:101], v[100:101], v[104:105]
	s_nop 0
	v_add_f32_e32 v82, v100, v101
	v_fmamk_f32 v82, v82, 0x3a800000, v152
	v_mul_f32_e32 v86, 0x4f800000, v82
	v_cmp_gt_f32_e32 vcc, s49, v82
	s_nop 1
	v_cndmask_b32_e32 v99, v82, v86, vcc
	v_sqrt_f32_e32 v100, v99
	v_mov_b32_e32 v82, v84
	v_mov_b32_e32 v86, v83
	v_mov_b32_e32 v83, v88
	v_add_u32_e32 v84, -1, v100
	v_add_u32_e32 v88, 1, v100
	v_fma_f32 v101, -v84, v100, v99
	v_fma_f32 v102, -v88, v100, v99
	v_cmp_ge_f32_e64 s[6:7], 0, v101
	s_nop 1
	v_cndmask_b32_e64 v84, v100, v84, s[6:7]
	v_cmp_lt_f32_e64 s[6:7], 0, v102
	s_nop 1
	v_cndmask_b32_e64 v84, v84, v88, s[6:7]
	v_mul_f32_e32 v88, 0x37800000, v84
	v_cndmask_b32_e32 v84, v84, v88, vcc
	v_cmp_class_f32_e32 vcc, v99, v153
	v_mov_b32_e32 v88, v85
	s_nop 0
	v_cndmask_b32_e32 v84, v84, v99, vcc
	v_div_scale_f32 v99, s[6:7], v84, v84, 1.0
	v_rcp_f32_e32 v100, v99
	v_div_scale_f32 v85, vcc, 1.0, v84, 1.0
	v_fma_f32 v101, -v99, v100, 1.0
	v_fmac_f32_e32 v100, v101, v100
	v_mul_f32_e32 v101, v85, v100
	v_fma_f32 v102, -v99, v101, v85
	v_fmac_f32_e32 v101, v102, v100
	v_fma_f32 v85, -v99, v101, v85
	v_div_fmas_f32 v85, v85, v100, v101
	v_div_fixup_f32 v84, v85, v84, 1.0
	v_pk_mul_f32 v[90:91], v[90:91], v[84:85] op_sel_hi:[1,0]
	v_pk_mul_f32 v[94:95], v[94:95], v[84:85] op_sel_hi:[1,0]
	v_pk_mul_f32 v[92:93], v[92:93], v[84:85] op_sel_hi:[1,0]
	v_pk_mul_f32 v[100:101], v[112:113], v[84:85] op_sel_hi:[1,0]
	v_pk_mul_f32 v[96:97], v[96:97], v[84:85] op_sel_hi:[1,0]
	v_pk_mul_f32 v[86:87], v[86:87], v[84:85] op_sel_hi:[1,0]
	v_pk_mul_f32 v[82:83], v[82:83], v[84:85] op_sel_hi:[1,0]
	v_pk_mul_f32 v[84:85], v[88:89], v[84:85] op_sel_hi:[1,0]
	v_mul_f32_e32 v89, 0xbfb8aa3b, v91
	v_mul_f32_e32 v99, 0xbfb8aa3b, v95
	v_mul_f32_e32 v102, 0xbfb8aa3b, v93
	v_exp_f32_e32 v89, v89
	v_exp_f32_e32 v99, v99
	v_exp_f32_e32 v102, v102
	v_mul_f32_e32 v104, 0xbfb8aa3b, v87
	v_add_f32_e32 v89, 1.0, v89
	v_add_f32_e32 v99, 1.0, v99
	v_add_f32_e32 v102, 1.0, v102
	v_rcp_f32_e32 v89, v89
	v_rcp_f32_e32 v99, v99
	v_rcp_f32_e32 v102, v102
	v_mul_f32_e32 v105, 0xbfb8aa3b, v83
	v_mul_f32_e32 v89, v91, v89
	v_mul_f32_e32 v91, v95, v99
	v_mul_f32_e32 v93, v93, v102
	v_exp_f32_e32 v104, v104
	v_exp_f32_e32 v105, v105
	v_mul_f32_e32 v89, v90, v89
	v_mul_f32_e32 v90, v94, v91
	v_mul_f32_e32 v91, v92, v93
	v_mul_f32_e32 v93, 0xbfb8aa3b, v85
	v_mul_f32_e32 v88, 0xbfb8aa3b, v101
	v_mul_f32_e32 v103, 0xbfb8aa3b, v97
	v_exp_f32_e32 v93, v93
	v_exp_f32_e32 v88, v88
	v_exp_f32_e32 v103, v103
	v_add_f32_e32 v104, 1.0, v104
	v_add_f32_e32 v94, 1.0, v105
	v_rcp_f32_e32 v104, v104
	v_rcp_f32_e32 v94, v94
	v_add_f32_e32 v93, 1.0, v93
	v_add_f32_e32 v88, 1.0, v88
	v_add_f32_e32 v103, 1.0, v103
	v_rcp_f32_e32 v93, v93
	v_rcp_f32_e32 v88, v88
	v_rcp_f32_e32 v103, v103
	v_mul_f32_e32 v87, v87, v104
	v_mul_f32_e32 v83, v83, v94
	v_mul_f32_e32 v86, v86, v87
	v_mul_f32_e32 v87, v82, v83
	v_mul_f32_e32 v82, v85, v93
	v_mul_f32_e32 v88, v101, v88
	v_mul_f32_e32 v95, v97, v103
	v_mul_f32_e32 v85, v84, v82
	v_mul_f32_e32 v88, v100, v88
	v_mul_f32_e32 v92, v96, v95
	v_cvt_pk_bf16_f32 v82, v88, v89
	v_cvt_pk_bf16_f32 v83, v90, v91
	v_cvt_pk_bf16_f32 v84, v92, v86
	v_cvt_pk_bf16_f32 v85, v87, v85
	v_mad_i64_i32 v[86:87], s[6:7], v98, s50, v[114:115]
	v_lshl_add_u64 v[86:87], v[86:87], 0, v[116:117]
	global_store_dwordx4 v[86:87], v[82:85], off
	v_mov_b32_e32 v100, v78
	v_mov_b32_e32 v101, v74
	v_or_b32_e32 v82, 48, v146
	v_ashrrev_i32_e32 v83, 31, v82
	v_lshlrev_b64 v[84:85], 6, v[82:83]
	v_lshl_add_u64 v[96:97], s[10:11], 0, v[84:85]
	s_waitcnt vmcnt(6)
	v_mov_b32_e32 v84, v192
	v_mov_b32_e32 v85, v193
	v_mov_b32_e32 v86, v194
	v_mov_b32_e32 v87, v195
	v_mov_b32_e32 v88, v196
	v_mov_b32_e32 v89, v197
	v_mov_b32_e32 v90, v198
	v_mov_b32_e32 v91, v199
	v_mov_b32_e32 v92, v200
	v_mov_b32_e32 v93, v201
	v_mov_b32_e32 v94, v202
	v_mov_b32_e32 v95, v203
	v_mov_b32_e32 v96, v204
	v_mov_b32_e32 v97, v205
	v_mov_b32_e32 v98, v206
	v_mov_b32_e32 v99, v207
	global_load_dwordx4 v[192:195], v[210:211], off offset:1024
	global_load_dwordx4 v[196:199], v[210:211], off offset:1040
	global_load_dwordx4 v[200:203], v[210:211], off offset:1056
	global_load_dwordx4 v[204:207], v[210:211], off offset:1072
	v_mov_b32_e32 v74, v79
	v_mov_b32_e32 v78, v80
	v_mov_b32_e32 v79, v76
	v_mov_b32_e32 v76, v81
	v_mov_b32_e32 v80, v85
	v_mov_b32_e32 v81, v86
	v_mov_b32_e32 v85, v87
	v_mov_b32_e32 v86, v89
	v_mov_b32_e32 v87, v90
	v_mov_b32_e32 v89, v91
	v_pk_add_f32 v[80:81], v[80:81], v[84:85]
	v_pk_add_f32 v[84:85], v[86:87], v[88:89]
	v_pk_add_f32 v[80:81], v[80:81], v[80:81] op_sel:[0,1] op_sel_hi:[1,0]
	v_pk_add_f32 v[84:85], v[84:85], v[84:85] op_sel:[0,1] op_sel_hi:[1,0]
	v_add_f32_e32 v90, v92, v93
	v_add_f32_e32 v92, v94, v95
	v_mov_b32_e32 v91, v98
	v_mov_b32_e32 v93, v99
	v_mov_b32_e32 v81, v96
	v_mov_b32_e32 v85, v97
	v_pk_add_f32 v[86:87], v[90:91], v[92:93]
	v_pk_add_f32 v[80:81], v[80:81], v[84:85]
	s_nop 0
	v_pk_add_f32 v[80:81], v[80:81], v[86:87]
	s_nop 0
	v_add_f32_e32 v80, v80, v81
	v_fmamk_f32 v80, v80, 0x3a800000, v152
	v_mul_f32_e32 v81, 0x4f800000, v80
	v_cmp_gt_f32_e32 vcc, s49, v80
	s_nop 1
	v_cndmask_b32_e32 v83, v80, v81, vcc
	v_sqrt_f32_e32 v84, v83
	v_mov_b32_e32 v80, v66
	v_mov_b32_e32 v81, v70
	v_mov_b32_e32 v70, v67
	v_add_u32_e32 v66, -1, v84
	v_add_u32_e32 v67, 1, v84
	v_fma_f32 v85, -v66, v84, v83
	v_fma_f32 v86, -v67, v84, v83
	v_cmp_ge_f32_e64 s[6:7], 0, v85
	s_nop 1
	v_cndmask_b32_e64 v66, v84, v66, s[6:7]
	v_cmp_lt_f32_e64 s[6:7], 0, v86
	s_nop 1
	v_cndmask_b32_e64 v66, v66, v67, s[6:7]
	v_mul_f32_e32 v67, 0x37800000, v66
	v_cndmask_b32_e32 v66, v66, v67, vcc
	v_cmp_class_f32_e32 vcc, v83, v153
	s_nop 1
	v_cndmask_b32_e32 v67, v66, v83, vcc
	v_div_scale_f32 v83, s[6:7], v67, v67, 1.0
	v_rcp_f32_e32 v84, v83
	v_mov_b32_e32 v66, v68
	v_div_scale_f32 v68, vcc, 1.0, v67, 1.0
	v_fma_f32 v85, -v83, v84, 1.0
	v_fmac_f32_e32 v84, v85, v84
	v_mul_f32_e32 v85, v68, v84
	v_fma_f32 v86, -v83, v85, v68
	v_fmac_f32_e32 v85, v86, v84
	v_fma_f32 v68, -v83, v85, v68
	v_div_fmas_f32 v68, v68, v84, v85
	v_div_fixup_f32 v68, v68, v67, 1.0
	v_pk_mul_f32 v[84:85], v[100:101], v[68:69] op_sel_hi:[1,0]
	v_pk_mul_f32 v[74:75], v[74:75], v[68:69] op_sel_hi:[1,0]
	v_mul_f32_e32 v67, 0xbfb8aa3b, v85
	v_mul_f32_e32 v83, 0xbfb8aa3b, v75
	v_exp_f32_e32 v67, v67
	v_pk_mul_f32 v[78:79], v[78:79], v[68:69] op_sel_hi:[1,0]
	v_exp_f32_e32 v83, v83
	v_mul_f32_e32 v86, 0xbfb8aa3b, v79
	v_exp_f32_e32 v86, v86
	v_add_f32_e32 v67, 1.0, v67
	v_add_f32_e32 v83, 1.0, v83
	v_rcp_f32_e32 v67, v67
	v_rcp_f32_e32 v83, v83
	v_add_f32_e32 v86, 1.0, v86
	v_rcp_f32_e32 v86, v86
	v_mul_f32_e32 v67, v85, v67
	v_mul_f32_e32 v75, v75, v83
	v_mul_f32_e32 v83, v84, v67
	v_mov_b32_e32 v67, v72
	v_pk_mul_f32 v[66:67], v[66:67], v[68:69] op_sel_hi:[1,0]
	v_mul_f32_e32 v79, v79, v86
	v_mul_f32_e32 v72, 0xbfb8aa3b, v67
	v_pk_mul_f32 v[70:71], v[70:71], v[68:69] op_sel_hi:[1,0]
	v_mul_f32_e32 v74, v74, v75
	v_mul_f32_e32 v75, v78, v79
	v_exp_f32_e32 v78, v72
	v_mov_b32_e32 v72, v69
	v_pk_mul_f32 v[76:77], v[76:77], v[68:69] op_sel_hi:[1,0]
	v_pk_mul_f32 v[80:81], v[80:81], v[68:69] op_sel_hi:[1,0]
	v_mul_f32_e32 v89, 0xbfb8aa3b, v71
	v_pk_mul_f32 v[68:69], v[72:73], v[68:69] op_sel_hi:[1,0]
	v_exp_f32_e32 v89, v89
	v_mul_f32_e32 v72, 0xbfb8aa3b, v69
	v_mul_f32_e32 v87, 0xbfb8aa3b, v77
	v_mul_f32_e32 v88, 0xbfb8aa3b, v81
	v_exp_f32_e32 v72, v72
	v_exp_f32_e32 v87, v87
	v_exp_f32_e32 v88, v88
	v_add_f32_e32 v89, 1.0, v89
	v_add_f32_e32 v73, 1.0, v78
	v_rcp_f32_e32 v89, v89
	v_rcp_f32_e32 v73, v73
	v_add_f32_e32 v72, 1.0, v72
	v_add_f32_e32 v87, 1.0, v87
	v_add_f32_e32 v88, 1.0, v88
	v_rcp_f32_e32 v72, v72
	v_rcp_f32_e32 v87, v87
	v_rcp_f32_e32 v88, v88
	v_mul_f32_e32 v71, v71, v89
	v_mul_f32_e32 v67, v67, v73
	v_mul_f32_e32 v70, v70, v71
	v_mul_f32_e32 v71, v66, v67
	v_mul_f32_e32 v66, v69, v72
	v_mul_f32_e32 v77, v77, v87
	v_mul_f32_e32 v81, v81, v88
	v_mul_f32_e32 v69, v68, v66
	v_mul_f32_e32 v76, v76, v77
	v_mul_f32_e32 v77, v80, v81
	v_cvt_pk_bf16_f32 v66, v83, v74
	v_cvt_pk_bf16_f32 v67, v75, v76
	v_cvt_pk_bf16_f32 v68, v77, v70
	v_cvt_pk_bf16_f32 v69, v71, v69
	v_mad_i64_i32 v[70:71], s[6:7], v82, s50, v[114:115]
	v_lshl_add_u64 v[70:71], v[70:71], 0, v[116:117]
	global_store_dwordx4 v[70:71], v[66:69], off
	v_mov_b32_e32 v85, v58
	v_mov_b32_e32 v58, v63
	v_add_u32_e32 v66, 0x80, v146
	v_ashrrev_i32_e32 v67, 31, v66
	v_lshlrev_b64 v[68:69], 6, v[66:67]
	v_lshl_add_u64 v[80:81], s[10:11], 0, v[68:69]
	s_waitcnt vmcnt(6)
	v_mov_b32_e32 v68, v176
	v_mov_b32_e32 v69, v177
	v_mov_b32_e32 v70, v178
	v_mov_b32_e32 v71, v179
	v_mov_b32_e32 v72, v180
	v_mov_b32_e32 v73, v181
	v_mov_b32_e32 v74, v182
	v_mov_b32_e32 v75, v183
	v_mov_b32_e32 v76, v184
	v_mov_b32_e32 v77, v185
	v_mov_b32_e32 v78, v186
	v_mov_b32_e32 v79, v187
	v_mov_b32_e32 v80, v188
	v_mov_b32_e32 v81, v189
	v_mov_b32_e32 v82, v190
	v_mov_b32_e32 v83, v191
	global_load_dwordx4 v[176:179], v[210:211], off offset:2048
	global_load_dwordx4 v[180:183], v[210:211], off offset:2064
	global_load_dwordx4 v[184:187], v[210:211], off offset:2080
	global_load_dwordx4 v[188:191], v[210:211], off offset:2096
	v_mov_b32_e32 v63, v60
	v_mov_b32_e32 v84, v62
	v_mov_b32_e32 v62, v64
	v_mov_b32_e32 v86, v69
	v_mov_b32_e32 v87, v70
	v_mov_b32_e32 v69, v71
	v_mov_b32_e32 v70, v73
	v_mov_b32_e32 v71, v74
	v_mov_b32_e32 v73, v75
	v_pk_add_f32 v[68:69], v[86:87], v[68:69]
	v_pk_add_f32 v[70:71], v[70:71], v[72:73]
	v_pk_add_f32 v[68:69], v[68:69], v[68:69] op_sel:[0,1] op_sel_hi:[1,0]
	v_pk_add_f32 v[70:71], v[70:71], v[70:71] op_sel:[0,1] op_sel_hi:[1,0]
	v_add_f32_e32 v74, v76, v77
	v_add_f32_e32 v76, v78, v79
	v_mov_b32_e32 v75, v82
	v_mov_b32_e32 v77, v83
	v_mov_b32_e32 v69, v80
	v_mov_b32_e32 v71, v81
	v_pk_add_f32 v[72:73], v[74:75], v[76:77]
	v_pk_add_f32 v[68:69], v[68:69], v[70:71]
	s_nop 0
	v_pk_add_f32 v[68:69], v[68:69], v[72:73]
	s_nop 0
	v_add_f32_e32 v60, v68, v69
	v_fmamk_f32 v60, v60, 0x3a800000, v152
	v_mul_f32_e32 v64, 0x4f800000, v60
	v_cmp_gt_f32_e32 vcc, s49, v60
	s_nop 1
	v_cndmask_b32_e32 v67, v60, v64, vcc
	v_sqrt_f32_e32 v68, v67
	v_mov_b32_e32 v64, v50
	v_mov_b32_e32 v60, v65
	v_mov_b32_e32 v65, v54
	v_add_u32_e32 v50, -1, v68
	v_add_u32_e32 v54, 1, v68
	v_fma_f32 v69, -v50, v68, v67
	v_fma_f32 v70, -v54, v68, v67
	v_cmp_ge_f32_e64 s[6:7], 0, v69
	s_nop 1
	v_cndmask_b32_e64 v50, v68, v50, s[6:7]
	v_cmp_lt_f32_e64 s[6:7], 0, v70
	s_nop 1
	v_cndmask_b32_e64 v50, v50, v54, s[6:7]
	v_mul_f32_e32 v54, 0x37800000, v50
	v_cndmask_b32_e32 v50, v50, v54, vcc
	v_cmp_class_f32_e32 vcc, v67, v153
	v_mov_b32_e32 v54, v51
	s_nop 0
	v_cndmask_b32_e32 v50, v50, v67, vcc
	v_div_scale_f32 v67, s[6:7], v50, v50, 1.0
	v_rcp_f32_e32 v68, v67
	v_div_scale_f32 v51, vcc, 1.0, v50, 1.0
	v_fma_f32 v69, -v67, v68, 1.0
	v_fmac_f32_e32 v68, v69, v68
	v_mul_f32_e32 v69, v51, v68
	v_fma_f32 v70, -v67, v69, v51
	v_fmac_f32_e32 v69, v70, v68
	v_fma_f32 v51, -v67, v69, v51
	v_div_fmas_f32 v51, v51, v68, v69
	v_div_fixup_f32 v50, v51, v50, 1.0
	v_pk_mul_f32 v[68:69], v[84:85], v[50:51] op_sel_hi:[1,0]
	v_pk_mul_f32 v[58:59], v[58:59], v[50:51] op_sel_hi:[1,0]
	v_pk_mul_f32 v[62:63], v[62:63], v[50:51] op_sel_hi:[1,0]
	v_pk_mul_f32 v[60:61], v[60:61], v[50:51] op_sel_hi:[1,0]
	v_pk_mul_f32 v[64:65], v[64:65], v[50:51] op_sel_hi:[1,0]
	v_pk_mul_f32 v[54:55], v[54:55], v[50:51] op_sel_hi:[1,0]
	v_mul_f32_e32 v51, 0xbfb8aa3b, v69
	v_mul_f32_e32 v67, 0xbfb8aa3b, v59
	v_mul_f32_e32 v71, 0xbfb8aa3b, v61
	v_mul_f32_e32 v72, 0xbfb8aa3b, v65
	v_exp_f32_e32 v51, v51
	v_exp_f32_e32 v67, v67
	v_exp_f32_e32 v71, v71
	v_exp_f32_e32 v72, v72
	v_mul_f32_e32 v70, 0xbfb8aa3b, v63
	v_exp_f32_e32 v70, v70
	v_add_f32_e32 v51, 1.0, v51
	v_add_f32_e32 v67, 1.0, v67
	v_add_f32_e32 v71, 1.0, v71
	v_add_f32_e32 v72, 1.0, v72
	v_rcp_f32_e32 v51, v51
	v_mul_f32_e32 v73, 0xbfb8aa3b, v55
	v_rcp_f32_e32 v67, v67
	v_rcp_f32_e32 v71, v71
	v_rcp_f32_e32 v72, v72
	v_exp_f32_e32 v73, v73
	v_add_f32_e32 v70, 1.0, v70
	v_rcp_f32_e32 v70, v70
	v_mul_f32_e32 v51, v69, v51
	v_mul_f32_e32 v59, v59, v67
	v_mul_f32_e32 v61, v61, v71
	v_mul_f32_e32 v67, v68, v51
	v_mul_f32_e32 v51, v65, v72
	v_mul_f32_e32 v68, v58, v59
	v_mul_f32_e32 v60, v60, v61
	v_mul_f32_e32 v61, v64, v51
	v_add_f32_e32 v51, 1.0, v73
	v_mov_b32_e32 v58, v52
	v_mov_b32_e32 v59, v56
	v_mul_f32_e32 v63, v63, v70
	v_pk_mul_f32 v[58:59], v[58:59], v[50:51] op_sel_hi:[1,0]
	v_mul_f32_e32 v62, v62, v63
	v_rcp_f32_e32 v63, v51
	v_mul_f32_e32 v51, 0xbfb8aa3b, v59
	v_mov_b32_e32 v56, v53
	v_exp_f32_e32 v52, v51
	v_pk_mul_f32 v[50:51], v[56:57], v[50:51] op_sel_hi:[1,0]
	v_mul_f32_e32 v55, v55, v63
	v_mul_f32_e32 v53, 0xbfb8aa3b, v51
	v_exp_f32_e32 v53, v53
	v_add_f32_e32 v52, 1.0, v52
	v_rcp_f32_e32 v52, v52
	v_mul_f32_e32 v54, v54, v55
	v_add_f32_e32 v53, 1.0, v53
	v_rcp_f32_e32 v53, v53
	v_mul_f32_e32 v52, v59, v52
	v_mul_f32_e32 v55, v58, v52
	v_mov_b32_e32 v69, v42
	v_mul_f32_e32 v51, v51, v53
	v_mul_f32_e32 v53, v50, v51
	v_cvt_pk_bf16_f32 v50, v67, v68
	v_cvt_pk_bf16_f32 v51, v62, v60
	v_cvt_pk_bf16_f32 v52, v61, v54
	v_cvt_pk_bf16_f32 v53, v55, v53
	v_mad_i64_i32 v[54:55], s[6:7], v66, s50, v[114:115]
	v_add_u32_e32 v66, 0x90, v146
	v_lshl_add_u64 v[54:55], v[54:55], 0, v[116:117]
	v_ashrrev_i32_e32 v67, 31, v66
	global_store_dwordx4 v[54:55], v[50:53], off
	v_mov_b32_e32 v42, v47
	v_mov_b32_e32 v68, v46
	v_lshlrev_b64 v[50:51], 6, v[66:67]
	v_lshl_add_u64 v[62:63], s[10:11], 0, v[50:51]
	s_waitcnt vmcnt(6)
	v_mov_b32_e32 v50, v192
	v_mov_b32_e32 v51, v193
	v_mov_b32_e32 v52, v194
	v_mov_b32_e32 v53, v195
	v_mov_b32_e32 v54, v196
	v_mov_b32_e32 v55, v197
	v_mov_b32_e32 v56, v198
	v_mov_b32_e32 v57, v199
	v_mov_b32_e32 v58, v200
	v_mov_b32_e32 v59, v201
	v_mov_b32_e32 v60, v202
	v_mov_b32_e32 v61, v203
	v_mov_b32_e32 v62, v204
	v_mov_b32_e32 v63, v205
	v_mov_b32_e32 v64, v206
	v_mov_b32_e32 v65, v207
	global_load_dwordx4 v[192:195], v[210:211], off offset:3072
	global_load_dwordx4 v[196:199], v[210:211], off offset:3088
	global_load_dwordx4 v[200:203], v[210:211], off offset:3104
	global_load_dwordx4 v[204:207], v[210:211], off offset:3120
	v_mov_b32_e32 v46, v48
	v_mov_b32_e32 v70, v51
	v_mov_b32_e32 v71, v52
	v_mov_b32_e32 v51, v53
	v_mov_b32_e32 v52, v55
	v_mov_b32_e32 v53, v56
	v_mov_b32_e32 v55, v57
	v_pk_add_f32 v[50:51], v[70:71], v[50:51]
	v_pk_add_f32 v[52:53], v[52:53], v[54:55]
	v_pk_add_f32 v[50:51], v[50:51], v[50:51] op_sel:[0,1] op_sel_hi:[1,0]
	v_pk_add_f32 v[52:53], v[52:53], v[52:53] op_sel:[0,1] op_sel_hi:[1,0]
	v_add_f32_e32 v56, v58, v59
	v_add_f32_e32 v58, v60, v61
	v_mov_b32_e32 v57, v64
	v_mov_b32_e32 v59, v65
	v_mov_b32_e32 v51, v62
	v_mov_b32_e32 v53, v63
	v_pk_add_f32 v[54:55], v[56:57], v[58:59]
	v_pk_add_f32 v[50:51], v[50:51], v[52:53]
	s_nop 0
	v_pk_add_f32 v[50:51], v[50:51], v[54:55]
	s_nop 0
	v_add_f32_e32 v47, v50, v51
	v_fmamk_f32 v47, v47, 0x3a800000, v152
	v_mul_f32_e32 v48, 0x4f800000, v47
	v_cmp_gt_f32_e32 vcc, s49, v47
	s_nop 1
	v_cndmask_b32_e32 v50, v47, v48, vcc
	v_sqrt_f32_e32 v51, v50
	v_mov_b32_e32 v48, v34
	v_mov_b32_e32 v47, v44
	v_mov_b32_e32 v44, v49
	v_add_u32_e32 v34, -1, v51
	v_add_u32_e32 v49, 1, v51
	v_fma_f32 v52, -v34, v51, v50
	v_fma_f32 v53, -v49, v51, v50
	v_cmp_ge_f32_e64 s[6:7], 0, v52
	s_nop 1
	v_cndmask_b32_e64 v34, v51, v34, s[6:7]
	v_cmp_lt_f32_e64 s[6:7], 0, v53
	s_nop 1
	v_cndmask_b32_e64 v34, v34, v49, s[6:7]
	v_mul_f32_e32 v49, 0x37800000, v34
	v_cndmask_b32_e32 v34, v34, v49, vcc
	v_cmp_class_f32_e32 vcc, v50, v153
	v_mov_b32_e32 v49, v38
	s_nop 0
	v_cndmask_b32_e32 v34, v34, v50, vcc
	v_div_scale_f32 v50, s[6:7], v34, v34, 1.0
	v_rcp_f32_e32 v51, v50
	v_div_scale_f32 v38, vcc, 1.0, v34, 1.0
	v_fma_f32 v52, -v50, v51, 1.0
	v_fmac_f32_e32 v51, v52, v51
	v_mul_f32_e32 v52, v38, v51
	v_fma_f32 v53, -v50, v52, v38
	v_fmac_f32_e32 v52, v53, v51
	v_fma_f32 v38, -v50, v52, v38
	v_div_fmas_f32 v38, v38, v51, v52
	v_div_fixup_f32 v34, v38, v34, 1.0
	v_pk_mul_f32 v[50:51], v[68:69], v[34:35] op_sel_hi:[1,0]
	v_pk_mul_f32 v[42:43], v[42:43], v[34:35] op_sel_hi:[1,0]
	v_mul_f32_e32 v38, 0xbfb8aa3b, v51
	v_mul_f32_e32 v52, 0xbfb8aa3b, v43
	v_exp_f32_e32 v38, v38
	v_exp_f32_e32 v52, v52
	v_pk_mul_f32 v[48:49], v[48:49], v[34:35] op_sel_hi:[1,0]
	v_pk_mul_f32 v[44:45], v[44:45], v[34:35] op_sel_hi:[1,0]
	v_add_f32_e32 v38, 1.0, v38
	v_mul_f32_e32 v55, 0xbfb8aa3b, v49
	v_add_f32_e32 v52, 1.0, v52
	v_rcp_f32_e32 v38, v38
	v_exp_f32_e32 v55, v55
	v_rcp_f32_e32 v52, v52
	v_mul_f32_e32 v54, 0xbfb8aa3b, v45
	v_pk_mul_f32 v[46:47], v[46:47], v[34:35] op_sel_hi:[1,0]
	v_exp_f32_e32 v54, v54
	v_mul_f32_e32 v53, 0xbfb8aa3b, v47
	v_mul_f32_e32 v38, v51, v38
	v_exp_f32_e32 v53, v53
	v_mul_f32_e32 v43, v43, v52
	v_mul_f32_e32 v50, v50, v38
	v_add_f32_e32 v38, 1.0, v55
	v_mul_f32_e32 v51, v42, v43
	v_rcp_f32_e32 v42, v38
	v_mov_b32_e32 v38, v35
	v_add_f32_e32 v54, 1.0, v54
	v_pk_mul_f32 v[38:39], v[38:39], v[34:35] op_sel_hi:[1,0]
	v_rcp_f32_e32 v54, v54
	v_mul_f32_e32 v35, 0xbfb8aa3b, v39
	v_add_f32_e32 v53, 1.0, v53
	v_exp_f32_e32 v35, v35
	v_rcp_f32_e32 v53, v53
	v_mul_f32_e32 v45, v45, v54
	v_mul_f32_e32 v42, v49, v42
	v_mul_f32_e32 v44, v44, v45
	v_mul_f32_e32 v45, v48, v42
	v_add_f32_e32 v35, 1.0, v35
	v_mov_b32_e32 v42, v36
	v_mov_b32_e32 v43, v40
	v_mul_f32_e32 v47, v47, v53
	v_pk_mul_f32 v[42:43], v[42:43], v[34:35] op_sel_hi:[1,0]
	v_mul_f32_e32 v46, v46, v47
	v_rcp_f32_e32 v47, v35
	v_mul_f32_e32 v35, 0xbfb8aa3b, v43
	v_mov_b32_e32 v40, v37
	v_exp_f32_e32 v36, v35
	v_pk_mul_f32 v[34:35], v[40:41], v[34:35] op_sel_hi:[1,0]
	v_mul_f32_e32 v39, v39, v47
	v_mul_f32_e32 v37, 0xbfb8aa3b, v35
	v_exp_f32_e32 v37, v37
	v_add_f32_e32 v36, 1.0, v36
	v_rcp_f32_e32 v36, v36
	v_mul_f32_e32 v38, v38, v39
	v_add_f32_e32 v37, 1.0, v37
	v_rcp_f32_e32 v37, v37
	v_mul_f32_e32 v36, v43, v36
	v_mul_f32_e32 v39, v42, v36
	v_mov_b32_e32 v53, v26
	v_mul_f32_e32 v35, v35, v37
	v_mul_f32_e32 v37, v34, v35
	v_cvt_pk_bf16_f32 v34, v50, v51
	v_cvt_pk_bf16_f32 v35, v46, v44
	v_cvt_pk_bf16_f32 v36, v45, v38
	v_cvt_pk_bf16_f32 v37, v39, v37
	v_mad_i64_i32 v[38:39], s[6:7], v66, s50, v[114:115]
	v_add_u32_e32 v50, 0xa0, v146
	v_lshl_add_u64 v[38:39], v[38:39], 0, v[116:117]
	v_ashrrev_i32_e32 v51, 31, v50
	global_store_dwordx4 v[38:39], v[34:37], off
	v_mov_b32_e32 v26, v31
	v_mov_b32_e32 v52, v30
	v_lshlrev_b64 v[34:35], 6, v[50:51]
	v_lshl_add_u64 v[46:47], s[10:11], 0, v[34:35]
	s_waitcnt vmcnt(6)
	v_mov_b32_e32 v34, v176
	v_mov_b32_e32 v35, v177
	v_mov_b32_e32 v36, v178
	v_mov_b32_e32 v37, v179
	v_mov_b32_e32 v38, v180
	v_mov_b32_e32 v39, v181
	v_mov_b32_e32 v40, v182
	v_mov_b32_e32 v41, v183
	v_mov_b32_e32 v42, v184
	v_mov_b32_e32 v43, v185
	v_mov_b32_e32 v44, v186
	v_mov_b32_e32 v45, v187
	v_mov_b32_e32 v46, v188
	v_mov_b32_e32 v47, v189
	v_mov_b32_e32 v48, v190
	v_mov_b32_e32 v49, v191
	v_mov_b32_e32 v30, v32
	v_mov_b32_e32 v54, v35
	v_mov_b32_e32 v55, v36
	v_mov_b32_e32 v35, v37
	v_mov_b32_e32 v36, v39
	v_mov_b32_e32 v37, v40
	v_mov_b32_e32 v39, v41
	v_pk_add_f32 v[34:35], v[54:55], v[34:35]
	v_pk_add_f32 v[36:37], v[36:37], v[38:39]
	v_pk_add_f32 v[34:35], v[34:35], v[34:35] op_sel:[0,1] op_sel_hi:[1,0]
	v_pk_add_f32 v[36:37], v[36:37], v[36:37] op_sel:[0,1] op_sel_hi:[1,0]
	v_add_f32_e32 v40, v42, v43
	v_add_f32_e32 v42, v44, v45
	v_mov_b32_e32 v41, v48
	v_mov_b32_e32 v43, v49
	v_mov_b32_e32 v35, v46
	v_mov_b32_e32 v37, v47
	v_pk_add_f32 v[38:39], v[40:41], v[42:43]
	v_pk_add_f32 v[34:35], v[34:35], v[36:37]
	s_nop 0
	v_pk_add_f32 v[34:35], v[34:35], v[38:39]
	s_nop 0
	v_add_f32_e32 v31, v34, v35
	v_fmamk_f32 v31, v31, 0x3a800000, v152
	v_mul_f32_e32 v32, 0x4f800000, v31
	v_cmp_gt_f32_e32 vcc, s49, v31
	s_nop 1
	v_cndmask_b32_e32 v34, v31, v32, vcc
	v_sqrt_f32_e32 v35, v34
	v_mov_b32_e32 v32, v18
	v_mov_b32_e32 v31, v28
	v_mov_b32_e32 v28, v33
	v_add_u32_e32 v18, -1, v35
	v_add_u32_e32 v33, 1, v35
	v_fma_f32 v36, -v18, v35, v34
	v_fma_f32 v37, -v33, v35, v34
	v_cmp_ge_f32_e64 s[6:7], 0, v36
	s_nop 1
	v_cndmask_b32_e64 v18, v35, v18, s[6:7]
	v_cmp_lt_f32_e64 s[6:7], 0, v37
	s_nop 1
	v_cndmask_b32_e64 v18, v18, v33, s[6:7]
	v_mul_f32_e32 v33, 0x37800000, v18
	v_cndmask_b32_e32 v18, v18, v33, vcc
	v_cmp_class_f32_e32 vcc, v34, v153
	v_mov_b32_e32 v33, v22
	s_nop 0
	v_cndmask_b32_e32 v18, v18, v34, vcc
	v_div_scale_f32 v34, s[6:7], v18, v18, 1.0
	v_rcp_f32_e32 v35, v34
	v_div_scale_f32 v22, vcc, 1.0, v18, 1.0
	v_fma_f32 v36, -v34, v35, 1.0
	v_fmac_f32_e32 v35, v36, v35
	v_mul_f32_e32 v36, v22, v35
	v_fma_f32 v37, -v34, v36, v22
	v_fmac_f32_e32 v36, v37, v35
	v_fma_f32 v22, -v34, v36, v22
	v_div_fmas_f32 v22, v22, v35, v36
	v_div_fixup_f32 v18, v22, v18, 1.0
	v_pk_mul_f32 v[26:27], v[26:27], v[18:19] op_sel_hi:[1,0]
	v_pk_mul_f32 v[34:35], v[52:53], v[18:19] op_sel_hi:[1,0]
	v_mul_f32_e32 v36, 0xbfb8aa3b, v27
	v_mul_f32_e32 v22, 0xbfb8aa3b, v35
	v_exp_f32_e32 v36, v36
	v_exp_f32_e32 v22, v22
	v_pk_mul_f32 v[30:31], v[30:31], v[18:19] op_sel_hi:[1,0]
	v_pk_mul_f32 v[28:29], v[28:29], v[18:19] op_sel_hi:[1,0]
	v_add_f32_e32 v36, 1.0, v36
	v_add_f32_e32 v22, 1.0, v22
	v_rcp_f32_e32 v36, v36
	v_mul_f32_e32 v37, 0xbfb8aa3b, v31
	v_rcp_f32_e32 v22, v22
	v_exp_f32_e32 v37, v37
	v_mul_f32_e32 v27, v27, v36
	v_mul_f32_e32 v38, 0xbfb8aa3b, v29
	v_mul_f32_e32 v22, v35, v22
	v_mul_f32_e32 v35, v26, v27
	v_pk_mul_f32 v[26:27], v[32:33], v[18:19] op_sel_hi:[1,0]
	v_add_f32_e32 v37, 1.0, v37
	v_mul_f32_e32 v34, v34, v22
	v_mul_f32_e32 v22, 0xbfb8aa3b, v27
	v_rcp_f32_e32 v37, v37
	v_exp_f32_e32 v22, v22
	v_exp_f32_e32 v38, v38
	v_mov_b32_e32 v36, v10
	v_mul_f32_e32 v31, v31, v37
	v_add_f32_e32 v22, 1.0, v22
	v_mul_f32_e32 v30, v30, v31
	v_rcp_f32_e32 v31, v22
	v_mov_b32_e32 v22, v19
	v_add_f32_e32 v38, 1.0, v38
	v_pk_mul_f32 v[22:23], v[22:23], v[18:19] op_sel_hi:[1,0]
	v_rcp_f32_e32 v38, v38
	v_mul_f32_e32 v19, 0xbfb8aa3b, v23
	v_exp_f32_e32 v19, v19
	v_mul_f32_e32 v27, v27, v31
	v_mul_f32_e32 v29, v29, v38
	v_mul_f32_e32 v28, v28, v29
	v_mul_f32_e32 v29, v26, v27
	v_add_f32_e32 v19, 1.0, v19
	v_mov_b32_e32 v26, v20
	v_mov_b32_e32 v27, v24
	v_pk_mul_f32 v[26:27], v[26:27], v[18:19] op_sel_hi:[1,0]
	v_rcp_f32_e32 v31, v19
	v_mul_f32_e32 v19, 0xbfb8aa3b, v27
	v_mov_b32_e32 v24, v21
	v_exp_f32_e32 v20, v19
	v_pk_mul_f32 v[18:19], v[24:25], v[18:19] op_sel_hi:[1,0]
	v_mul_f32_e32 v23, v23, v31
	v_mul_f32_e32 v21, 0xbfb8aa3b, v19
	v_exp_f32_e32 v21, v21
	v_add_f32_e32 v20, 1.0, v20
	v_rcp_f32_e32 v20, v20
	v_mul_f32_e32 v22, v22, v23
	v_add_f32_e32 v21, 1.0, v21
	v_rcp_f32_e32 v21, v21
	v_mul_f32_e32 v20, v27, v20
	v_mul_f32_e32 v23, v26, v20
	v_mov_b32_e32 v37, v14
	v_mul_f32_e32 v19, v19, v21
	v_mul_f32_e32 v21, v18, v19
	v_cvt_pk_bf16_f32 v18, v34, v35
	v_cvt_pk_bf16_f32 v19, v30, v28
	v_cvt_pk_bf16_f32 v20, v29, v22
	v_cvt_pk_bf16_f32 v21, v23, v21
	v_mad_i64_i32 v[22:23], s[6:7], v50, s50, v[114:115]
	v_add_u32_e32 v34, 0xb0, v146
	v_lshl_add_u64 v[22:23], v[22:23], 0, v[116:117]
	v_ashrrev_i32_e32 v35, 31, v34
	global_store_dwordx4 v[22:23], v[18:21], off
	s_nop 1
	v_lshlrev_b64 v[18:19], 6, v[34:35]
	v_lshl_add_u64 v[30:31], s[10:11], 0, v[18:19]
	s_waitcnt vmcnt(2)
	v_mov_b32_e32 v18, v192
	v_mov_b32_e32 v19, v193
	v_mov_b32_e32 v20, v194
	v_mov_b32_e32 v21, v195
	v_mov_b32_e32 v22, v196
	v_mov_b32_e32 v23, v197
	v_mov_b32_e32 v24, v198
	v_mov_b32_e32 v25, v199
	v_mov_b32_e32 v26, v200
	v_mov_b32_e32 v27, v201
	v_mov_b32_e32 v28, v202
	v_mov_b32_e32 v29, v203
	v_mov_b32_e32 v30, v204
	v_mov_b32_e32 v31, v205
	v_mov_b32_e32 v32, v206
	v_mov_b32_e32 v33, v207
	v_mov_b32_e32 v38, v19
	v_mov_b32_e32 v39, v20
	v_mov_b32_e32 v19, v21
	v_mov_b32_e32 v20, v23
	v_mov_b32_e32 v21, v24
	v_mov_b32_e32 v23, v25
	v_pk_add_f32 v[18:19], v[38:39], v[18:19]
	v_pk_add_f32 v[20:21], v[20:21], v[22:23]
	v_pk_add_f32 v[18:19], v[18:19], v[18:19] op_sel:[0,1] op_sel_hi:[1,0]
	v_pk_add_f32 v[20:21], v[20:21], v[20:21] op_sel:[0,1] op_sel_hi:[1,0]
	v_add_f32_e32 v24, v26, v27
	v_add_f32_e32 v26, v28, v29
	v_mov_b32_e32 v25, v32
	v_mov_b32_e32 v27, v33
	v_mov_b32_e32 v19, v30
	v_mov_b32_e32 v21, v31
	v_pk_add_f32 v[22:23], v[24:25], v[26:27]
	v_pk_add_f32 v[18:19], v[18:19], v[20:21]
	s_nop 0
	v_pk_add_f32 v[18:19], v[18:19], v[22:23]
	s_nop 0
	v_add_f32_e32 v10, v18, v19
	v_fmamk_f32 v10, v10, 0x3a800000, v152
	v_mul_f32_e32 v14, 0x4f800000, v10
	v_cmp_gt_f32_e32 vcc, s49, v10
	s_nop 1
	v_cndmask_b32_e32 v18, v10, v14, vcc
	v_sqrt_f32_e32 v19, v18
	v_mov_b32_e32 v10, v12
	v_mov_b32_e32 v14, v11
	v_mov_b32_e32 v11, v16
	v_add_u32_e32 v12, -1, v19
	v_add_u32_e32 v16, 1, v19
	v_fma_f32 v20, -v12, v19, v18
	v_fma_f32 v21, -v16, v19, v18
	v_cmp_ge_f32_e64 s[6:7], 0, v20
	s_nop 1
	v_cndmask_b32_e64 v12, v19, v12, s[6:7]
	v_cmp_lt_f32_e64 s[6:7], 0, v21
	s_nop 1
	v_cndmask_b32_e64 v12, v12, v16, s[6:7]
	v_mul_f32_e32 v16, 0x37800000, v12
	v_cndmask_b32_e32 v12, v12, v16, vcc
	v_cmp_class_f32_e32 vcc, v18, v153
	v_mov_b32_e32 v16, v13
	s_nop 0
	v_cndmask_b32_e32 v12, v12, v18, vcc
	v_div_scale_f32 v18, s[6:7], v12, v12, 1.0
	v_rcp_f32_e32 v19, v18
	v_div_scale_f32 v13, vcc, 1.0, v12, 1.0
	v_fma_f32 v20, -v18, v19, 1.0
	v_fmac_f32_e32 v19, v20, v19
	v_mul_f32_e32 v20, v13, v19
	v_fma_f32 v21, -v18, v20, v13
	v_fmac_f32_e32 v20, v21, v19
	v_fma_f32 v13, -v18, v20, v13
	v_div_fmas_f32 v13, v13, v19, v20
	v_div_fixup_f32 v12, v13, v12, 1.0
	v_pk_mul_f32 v[18:19], v[36:37], v[12:13] op_sel_hi:[1,0]
	v_pk_mul_f32 v[14:15], v[14:15], v[12:13] op_sel_hi:[1,0]
	v_pk_mul_f32 v[10:11], v[10:11], v[12:13] op_sel_hi:[1,0]
	v_pk_mul_f32 v[16:17], v[16:17], v[12:13] op_sel_hi:[1,0]
	v_mul_f32_e32 v13, 0xbfb8aa3b, v19
	v_mul_f32_e32 v20, 0xbfb8aa3b, v15
	v_exp_f32_e32 v13, v13
	v_exp_f32_e32 v20, v20
	v_mul_f32_e32 v21, 0xbfb8aa3b, v11
	v_mul_f32_e32 v22, 0xbfb8aa3b, v17
	v_add_f32_e32 v13, 1.0, v13
	v_add_f32_e32 v20, 1.0, v20
	v_rcp_f32_e32 v13, v13
	v_rcp_f32_e32 v20, v20
	v_exp_f32_e32 v21, v21
	v_exp_f32_e32 v22, v22
	v_mul_f32_e32 v13, v19, v13
	v_mul_f32_e32 v15, v15, v20
	v_mul_f32_e32 v13, v18, v13
	v_mul_f32_e32 v18, v14, v15
	v_add_f32_e32 v14, 1.0, v21
	v_rcp_f32_e32 v19, v14
	v_add_f32_e32 v14, 1.0, v22
	v_rcp_f32_e32 v20, v14
	v_mov_b32_e32 v14, v2
	v_mov_b32_e32 v15, v6
	v_pk_mul_f32 v[14:15], v[14:15], v[12:13] op_sel_hi:[1,0]
	v_mul_f32_e32 v6, v11, v19
	v_mul_f32_e32 v2, 0xbfb8aa3b, v15
	v_exp_f32_e32 v2, v2
	v_mul_f32_e32 v10, v10, v6
	v_mov_b32_e32 v6, v3
	v_mul_f32_e32 v11, v17, v20
	v_add_f32_e32 v2, 1.0, v2
	v_rcp_f32_e32 v17, v2
	v_pk_mul_f32 v[2:3], v[6:7], v[12:13] op_sel_hi:[1,0]
	v_mul_f32_e32 v11, v16, v11
	v_mul_f32_e32 v6, 0xbfb8aa3b, v3
	v_exp_f32_e32 v6, v6
	v_mul_f32_e32 v7, v15, v17
	v_mul_f32_e32 v14, v14, v7
	v_mov_b32_e32 v7, v8
	v_add_f32_e32 v6, 1.0, v6
	v_rcp_f32_e32 v15, v6
	v_mov_b32_e32 v6, v4
	v_pk_mul_f32 v[6:7], v[6:7], v[12:13] op_sel_hi:[1,0]
	v_mov_b32_e32 v8, v5
	v_mul_f32_e32 v4, 0xbfb8aa3b, v7
	v_exp_f32_e32 v16, v4
	v_pk_mul_f32 v[4:5], v[8:9], v[12:13] op_sel_hi:[1,0]
	v_mul_f32_e32 v3, v3, v15
	v_mul_f32_e32 v8, 0xbfb8aa3b, v5
	v_exp_f32_e32 v8, v8
	v_add_f32_e32 v9, 1.0, v16
	v_rcp_f32_e32 v9, v9
	v_mul_f32_e32 v12, v2, v3
	v_add_f32_e32 v8, 1.0, v8
	v_rcp_f32_e32 v8, v8
	v_mul_f32_e32 v2, v7, v9
	v_mul_f32_e32 v6, v6, v2
	s_andn2_b64 vcc, exec, s[4:5]
	v_mul_f32_e32 v2, v5, v8
	v_mul_f32_e32 v5, v4, v2
	v_cvt_pk_bf16_f32 v2, v13, v18
	v_cvt_pk_bf16_f32 v3, v10, v11
	v_cvt_pk_bf16_f32 v4, v14, v12
	v_cvt_pk_bf16_f32 v5, v6, v5
	v_mad_i64_i32 v[6:7], s[6:7], v34, s50, v[114:115]
	v_lshl_add_u64 v[6:7], v[6:7], 0, v[116:117]
	s_mov_b64 s[4:5], -1
	global_store_dwordx4 v[6:7], v[2:5], off
	s_cbranch_vccnz .LBB0_2425
	s_andn2_b64 vcc, exec, s[2:3]
	s_cbranch_vccnz .LBB0_2424
	s_barrier
	s_branch .LBB0_2424
